# GEMM K-loops: LDS-DMA loads use SGPR-base addressing (16 fewer 64-bit VALU adds per trip, K-step bases by SALU)
# speedup vs baseline: 1.0119x; 1.0044x over previous
.LBB0_151:
	ds_read_b128 v[144:147], v157
	ds_read_b128 v[162:165], v157 offset:1024
	ds_read_b128 v[166:169], v157 offset:2048
	ds_read_b128 v[170:173], v157 offset:3072
	ds_read_b128 v[174:177], v159
	ds_read_b128 v[178:181], v159 offset:1024
	ds_read_b128 v[182:185], v159 offset:2048
	ds_read_b128 v[186:189], v159 offset:3072
	s_add_u32 s50, s48, 0xfff80080
	s_addc_u32 s51, s49, -1
	s_cmp_eq_u32 s76, 28
	s_cselect_b32 s59, s19, s51
	s_cselect_b32 s58, s72, s50
	s_cselect_b32 s51, s15, s75
	s_cselect_b32 s50, s73, s74
	s_add_i32 m0, s47, 0xc000
	ds_read_b128 v[190:193], v160
	ds_read_b128 v[194:197], v160 offset:1024
	ds_read_b128 v[198:201], v160 offset:2048
	ds_read_b128 v[202:205], v160 offset:3072
	ds_read_b128 v[206:209], v160 offset:4096
	ds_read_b128 v[210:213], v160 offset:5120
	ds_read_b128 v[214:217], v160 offset:6144
	ds_read_b128 v[218:221], v160 offset:7168
	global_load_lds_dwordx4 v136, s[48:49]
	s_add_i32 m0, s47, 0xe000
	s_nop 0
	global_load_lds_dwordx4 v138, s[48:49]
	s_waitcnt vmcnt(8)
	s_waitcnt lgkmcnt(0)
	s_barrier
	s_setprio 3
	s_waitcnt lgkmcnt(0)
	v_mfma_f32_16x16x32_bf16 v[124:127], v[144:147], v[190:193], v[124:127]
	v_mfma_f32_16x16x32_bf16 v[120:123], v[166:169], v[190:193], v[120:123]
	v_mfma_f32_16x16x32_bf16 v[116:119], v[144:147], v[198:201], v[116:119]
	v_mfma_f32_16x16x32_bf16 v[112:115], v[166:169], v[198:201], v[112:115]
	v_mfma_f32_16x16x32_bf16 v[92:95], v[144:147], v[206:209], v[92:95]
	v_mfma_f32_16x16x32_bf16 v[88:91], v[166:169], v[206:209], v[88:91]
	v_mfma_f32_16x16x32_bf16 v[76:79], v[144:147], v[214:217], v[76:79]
	v_mfma_f32_16x16x32_bf16 v[72:75], v[166:169], v[214:217], v[72:75]
	v_mfma_f32_16x16x32_bf16 v[124:127], v[162:165], v[194:197], v[124:127]
	v_mfma_f32_16x16x32_bf16 v[120:123], v[170:173], v[194:197], v[120:123]
	v_mfma_f32_16x16x32_bf16 v[116:119], v[162:165], v[202:205], v[116:119]
	v_mfma_f32_16x16x32_bf16 v[112:115], v[170:173], v[202:205], v[112:115]
	v_mfma_f32_16x16x32_bf16 v[92:95], v[162:165], v[210:213], v[92:95]
	v_mfma_f32_16x16x32_bf16 v[88:91], v[170:173], v[210:213], v[88:91]
	v_mfma_f32_16x16x32_bf16 v[76:79], v[162:165], v[218:221], v[76:79]
	v_mfma_f32_16x16x32_bf16 v[72:75], v[170:173], v[218:221], v[72:75]
	s_setprio 0
	s_setprio 3
	v_mfma_f32_16x16x32_bf16 v[108:111], v[174:177], v[190:193], v[108:111]
	v_mfma_f32_16x16x32_bf16 v[104:107], v[182:185], v[190:193], v[104:107]
	v_mfma_f32_16x16x32_bf16 v[100:103], v[174:177], v[198:201], v[100:103]
	v_mfma_f32_16x16x32_bf16 v[96:99], v[182:185], v[198:201], v[96:99]
	v_mfma_f32_16x16x32_bf16 v[84:87], v[174:177], v[206:209], v[84:87]
	v_mfma_f32_16x16x32_bf16 v[80:83], v[182:185], v[206:209], v[80:83]
	v_mfma_f32_16x16x32_bf16 v[68:71], v[174:177], v[214:217], v[68:71]
	v_mfma_f32_16x16x32_bf16 v[64:67], v[182:185], v[214:217], v[64:67]
	v_mfma_f32_16x16x32_bf16 v[108:111], v[178:181], v[194:197], v[108:111]
	v_mfma_f32_16x16x32_bf16 v[104:107], v[186:189], v[194:197], v[104:107]
	v_mfma_f32_16x16x32_bf16 v[100:103], v[178:181], v[202:205], v[100:103]
	v_mfma_f32_16x16x32_bf16 v[96:99], v[186:189], v[202:205], v[96:99]
	v_mfma_f32_16x16x32_bf16 v[84:87], v[178:181], v[210:213], v[84:87]
	v_mfma_f32_16x16x32_bf16 v[80:83], v[186:189], v[210:213], v[80:83]
	v_mfma_f32_16x16x32_bf16 v[68:71], v[178:181], v[218:221], v[68:71]
	v_mfma_f32_16x16x32_bf16 v[64:67], v[186:189], v[218:221], v[64:67]
	s_setprio 0
	s_barrier
	s_add_u32 s98, s50, s10
	s_addc_u32 s99, s51, s11
	s_add_u32 s100, s58, s10
	s_addc_u32 s101, s59, s11
	s_add_i32 s77, s68, s89
	s_mov_b32 m0, s77
	ds_read_b128 v[190:193], v160 offset:16384
	ds_read_b128 v[194:197], v160 offset:17408
	ds_read_b128 v[198:201], v160 offset:18432
	ds_read_b128 v[202:205], v160 offset:19456
	ds_read_b128 v[206:209], v160 offset:20480
	ds_read_b128 v[210:213], v160 offset:21504
	ds_read_b128 v[214:217], v160 offset:22528
	ds_read_b128 v[218:221], v160 offset:23552
	global_load_lds_dwordx4 v128, s[50:51]
	s_add_i32 m0, s77, 0x2000
	s_add_u32 s78, s50, 0x80000
	s_addc_u32 s79, s51, 0
	s_add_i32 s77, s69, s89
	global_load_lds_dwordx4 v130, s[50:51]
	s_mov_b32 m0, s77
	s_nop 0
	global_load_lds_dwordx4 v128, s[78:79]
	s_add_i32 m0, s77, 0x2000
	s_nop 0
	global_load_lds_dwordx4 v130, s[78:79]
	s_mov_b32 m0, s47
	s_nop 0
	global_load_lds_dwordx4 v134, s[58:59]
	s_mov_b32 m0, s56
	s_nop 0
	global_load_lds_dwordx4 v132, s[58:59]
	s_waitcnt vmcnt(8)
	s_waitcnt lgkmcnt(0)
	s_barrier
	s_setprio 3
	s_waitcnt lgkmcnt(0)
	v_mfma_f32_16x16x32_bf16 v[60:63], v[144:147], v[190:193], v[60:63]
	v_mfma_f32_16x16x32_bf16 v[56:59], v[166:169], v[190:193], v[56:59]
	v_mfma_f32_16x16x32_bf16 v[44:47], v[144:147], v[198:201], v[44:47]
	v_mfma_f32_16x16x32_bf16 v[40:43], v[166:169], v[198:201], v[40:43]
	v_mfma_f32_16x16x32_bf16 v[28:31], v[144:147], v[206:209], v[28:31]
	v_mfma_f32_16x16x32_bf16 v[24:27], v[166:169], v[206:209], v[24:27]
	v_mfma_f32_16x16x32_bf16 v[12:15], v[144:147], v[214:217], v[12:15]
	v_mfma_f32_16x16x32_bf16 v[8:11], v[166:169], v[214:217], v[8:11]
	v_mfma_f32_16x16x32_bf16 v[60:63], v[162:165], v[194:197], v[60:63]
	v_mfma_f32_16x16x32_bf16 v[56:59], v[170:173], v[194:197], v[56:59]
	v_mfma_f32_16x16x32_bf16 v[44:47], v[162:165], v[202:205], v[44:47]
	v_mfma_f32_16x16x32_bf16 v[40:43], v[170:173], v[202:205], v[40:43]
	v_mfma_f32_16x16x32_bf16 v[28:31], v[162:165], v[210:213], v[28:31]
	v_mfma_f32_16x16x32_bf16 v[24:27], v[170:173], v[210:213], v[24:27]
	v_mfma_f32_16x16x32_bf16 v[12:15], v[162:165], v[218:221], v[12:15]
	v_mfma_f32_16x16x32_bf16 v[8:11], v[170:173], v[218:221], v[8:11]
	s_setprio 0
	s_setprio 3
	v_mfma_f32_16x16x32_bf16 v[52:55], v[174:177], v[190:193], v[52:55]
	v_mfma_f32_16x16x32_bf16 v[48:51], v[182:185], v[190:193], v[48:51]
	v_mfma_f32_16x16x32_bf16 v[36:39], v[174:177], v[198:201], v[36:39]
	v_mfma_f32_16x16x32_bf16 v[32:35], v[182:185], v[198:201], v[32:35]
	v_mfma_f32_16x16x32_bf16 v[20:23], v[174:177], v[206:209], v[20:23]
	v_mfma_f32_16x16x32_bf16 v[16:19], v[182:185], v[206:209], v[16:19]
	v_mfma_f32_16x16x32_bf16 v[4:7], v[174:177], v[214:217], v[4:7]
	v_mfma_f32_16x16x32_bf16 v[0:3], v[182:185], v[214:217], v[0:3]
	v_mfma_f32_16x16x32_bf16 v[52:55], v[178:181], v[194:197], v[52:55]
	v_mfma_f32_16x16x32_bf16 v[48:51], v[186:189], v[194:197], v[48:51]
	v_mfma_f32_16x16x32_bf16 v[36:39], v[178:181], v[202:205], v[36:39]
	v_mfma_f32_16x16x32_bf16 v[32:35], v[186:189], v[202:205], v[32:35]
	v_mfma_f32_16x16x32_bf16 v[20:23], v[178:181], v[210:213], v[20:23]
	v_mfma_f32_16x16x32_bf16 v[16:19], v[186:189], v[210:213], v[16:19]
	v_mfma_f32_16x16x32_bf16 v[4:7], v[178:181], v[218:221], v[4:7]
	v_mfma_f32_16x16x32_bf16 v[0:3], v[186:189], v[218:221], v[0:3]
	s_setprio 0
	s_barrier
	s_add_i32 s77, 0, 0x18000
	v_add_u32_e32 v150, s77, v153
	s_add_i32 s78, 0, 0x1c000
	ds_read_b128 v[144:147], v150
	ds_read_b128 v[162:165], v150 offset:1024
	ds_read_b128 v[166:169], v150 offset:2048
	ds_read_b128 v[170:173], v150 offset:3072
	v_add_u32_e32 v150, s78, v153
	ds_read_b128 v[174:177], v150
	ds_read_b128 v[178:181], v150 offset:1024
	ds_read_b128 v[182:185], v150 offset:2048
	ds_read_b128 v[186:189], v150 offset:3072
	s_add_u32 s58, s58, 0x80000
	s_addc_u32 s59, s59, 0
	s_mov_b32 m0, s57
	ds_read_b128 v[190:193], v160 offset:32768
	ds_read_b128 v[194:197], v160 offset:33792
	ds_read_b128 v[198:201], v160 offset:34816
	ds_read_b128 v[202:205], v160 offset:35840
	ds_read_b128 v[206:209], v160 offset:36864
	ds_read_b128 v[210:213], v160 offset:37888
	ds_read_b128 v[214:217], v160 offset:38912
	ds_read_b128 v[218:221], v160 offset:39936
	global_load_lds_dwordx4 v134, s[58:59]
	s_mov_b32 m0, s61
	s_nop 0
	global_load_lds_dwordx4 v132, s[58:59]
	s_waitcnt vmcnt(8)
	s_waitcnt lgkmcnt(0)
	s_barrier
	s_setprio 3
	s_waitcnt lgkmcnt(0)
	v_mfma_f32_16x16x32_bf16 v[124:127], v[144:147], v[190:193], v[124:127]
	v_mfma_f32_16x16x32_bf16 v[120:123], v[166:169], v[190:193], v[120:123]
	v_mfma_f32_16x16x32_bf16 v[116:119], v[144:147], v[198:201], v[116:119]
	v_mfma_f32_16x16x32_bf16 v[112:115], v[166:169], v[198:201], v[112:115]
	v_mfma_f32_16x16x32_bf16 v[92:95], v[144:147], v[206:209], v[92:95]
	v_mfma_f32_16x16x32_bf16 v[88:91], v[166:169], v[206:209], v[88:91]
	v_mfma_f32_16x16x32_bf16 v[76:79], v[144:147], v[214:217], v[76:79]
	v_mfma_f32_16x16x32_bf16 v[72:75], v[166:169], v[214:217], v[72:75]
	v_mfma_f32_16x16x32_bf16 v[124:127], v[162:165], v[194:197], v[124:127]
	v_mfma_f32_16x16x32_bf16 v[120:123], v[170:173], v[194:197], v[120:123]
	v_mfma_f32_16x16x32_bf16 v[116:119], v[162:165], v[202:205], v[116:119]
	v_mfma_f32_16x16x32_bf16 v[112:115], v[170:173], v[202:205], v[112:115]
	v_mfma_f32_16x16x32_bf16 v[92:95], v[162:165], v[210:213], v[92:95]
	v_mfma_f32_16x16x32_bf16 v[88:91], v[170:173], v[210:213], v[88:91]
	v_mfma_f32_16x16x32_bf16 v[76:79], v[162:165], v[218:221], v[76:79]
	v_mfma_f32_16x16x32_bf16 v[72:75], v[170:173], v[218:221], v[72:75]
	s_setprio 0
	s_setprio 3
	v_mfma_f32_16x16x32_bf16 v[108:111], v[174:177], v[190:193], v[108:111]
	v_mfma_f32_16x16x32_bf16 v[104:107], v[182:185], v[190:193], v[104:107]
	v_mfma_f32_16x16x32_bf16 v[100:103], v[174:177], v[198:201], v[100:103]
	v_mfma_f32_16x16x32_bf16 v[96:99], v[182:185], v[198:201], v[96:99]
	v_mfma_f32_16x16x32_bf16 v[84:87], v[174:177], v[206:209], v[84:87]
	v_mfma_f32_16x16x32_bf16 v[80:83], v[182:185], v[206:209], v[80:83]
	v_mfma_f32_16x16x32_bf16 v[68:71], v[174:177], v[214:217], v[68:71]
	v_mfma_f32_16x16x32_bf16 v[64:67], v[182:185], v[214:217], v[64:67]
	v_mfma_f32_16x16x32_bf16 v[108:111], v[178:181], v[194:197], v[108:111]
	v_mfma_f32_16x16x32_bf16 v[104:107], v[186:189], v[194:197], v[104:107]
	v_mfma_f32_16x16x32_bf16 v[100:103], v[178:181], v[202:205], v[100:103]
	v_mfma_f32_16x16x32_bf16 v[96:99], v[186:189], v[202:205], v[96:99]
	v_mfma_f32_16x16x32_bf16 v[84:87], v[178:181], v[210:213], v[84:87]
	v_mfma_f32_16x16x32_bf16 v[80:83], v[186:189], v[210:213], v[80:83]
	v_mfma_f32_16x16x32_bf16 v[68:71], v[178:181], v[218:221], v[68:71]
	v_mfma_f32_16x16x32_bf16 v[64:67], v[186:189], v[218:221], v[64:67]
	s_setprio 0
	s_barrier
	s_add_i32 s58, s77, s89
	s_mov_b32 m0, s58
	ds_read_b128 v[190:193], v160 offset:49152
	ds_read_b128 v[194:197], v160 offset:50176
	ds_read_b128 v[198:201], v160 offset:51200
	ds_read_b128 v[202:205], v160 offset:52224
	ds_read_b128 v[206:209], v160 offset:53248
	ds_read_b128 v[210:213], v160 offset:54272
	ds_read_b128 v[214:217], v160 offset:55296
	ds_read_b128 v[218:221], v160 offset:56320
	global_load_lds_dwordx4 v128, s[98:99]
	s_add_i32 m0, s58, 0x2000
	s_add_u32 s50, s50, 0x80080
	s_addc_u32 s51, s51, 0
	s_add_i32 s58, s78, s89
	global_load_lds_dwordx4 v130, s[98:99]
	s_mov_b32 m0, s58
	s_nop 0
	global_load_lds_dwordx4 v128, s[50:51]
	s_add_i32 m0, s58, 0x2000
	s_nop 0
	global_load_lds_dwordx4 v130, s[50:51]
	s_mov_b32 m0, s64
	s_nop 0
	global_load_lds_dwordx4 v134, s[100:101]
	s_mov_b32 m0, s65
	s_nop 0
	global_load_lds_dwordx4 v132, s[100:101]
	s_waitcnt vmcnt(8)
	s_waitcnt lgkmcnt(0)
	s_barrier
	s_setprio 3
	s_waitcnt lgkmcnt(0)
	v_mfma_f32_16x16x32_bf16 v[60:63], v[144:147], v[190:193], v[60:63]
	v_mfma_f32_16x16x32_bf16 v[56:59], v[166:169], v[190:193], v[56:59]
	v_mfma_f32_16x16x32_bf16 v[44:47], v[144:147], v[198:201], v[44:47]
	v_mfma_f32_16x16x32_bf16 v[40:43], v[166:169], v[198:201], v[40:43]
	v_mfma_f32_16x16x32_bf16 v[28:31], v[144:147], v[206:209], v[28:31]
	v_mfma_f32_16x16x32_bf16 v[24:27], v[166:169], v[206:209], v[24:27]
	v_mfma_f32_16x16x32_bf16 v[12:15], v[144:147], v[214:217], v[12:15]
	v_mfma_f32_16x16x32_bf16 v[8:11], v[166:169], v[214:217], v[8:11]
	v_mfma_f32_16x16x32_bf16 v[60:63], v[162:165], v[194:197], v[60:63]
	v_mfma_f32_16x16x32_bf16 v[56:59], v[170:173], v[194:197], v[56:59]
	v_mfma_f32_16x16x32_bf16 v[44:47], v[162:165], v[202:205], v[44:47]
	v_mfma_f32_16x16x32_bf16 v[40:43], v[170:173], v[202:205], v[40:43]
	v_mfma_f32_16x16x32_bf16 v[28:31], v[162:165], v[210:213], v[28:31]
	v_mfma_f32_16x16x32_bf16 v[24:27], v[170:173], v[210:213], v[24:27]
	v_mfma_f32_16x16x32_bf16 v[12:15], v[162:165], v[218:221], v[12:15]
	v_mfma_f32_16x16x32_bf16 v[8:11], v[170:173], v[218:221], v[8:11]
	s_setprio 0
	s_setprio 3
	v_mfma_f32_16x16x32_bf16 v[52:55], v[174:177], v[190:193], v[52:55]
	v_mfma_f32_16x16x32_bf16 v[48:51], v[182:185], v[190:193], v[48:51]
	v_mfma_f32_16x16x32_bf16 v[36:39], v[174:177], v[198:201], v[36:39]
	v_mfma_f32_16x16x32_bf16 v[32:35], v[182:185], v[198:201], v[32:35]
	v_mfma_f32_16x16x32_bf16 v[20:23], v[174:177], v[206:209], v[20:23]
	v_mfma_f32_16x16x32_bf16 v[16:19], v[182:185], v[206:209], v[16:19]
	v_mfma_f32_16x16x32_bf16 v[4:7], v[174:177], v[214:217], v[4:7]
	v_mfma_f32_16x16x32_bf16 v[0:3], v[182:185], v[214:217], v[0:3]
	v_mfma_f32_16x16x32_bf16 v[52:55], v[178:181], v[194:197], v[52:55]
	v_mfma_f32_16x16x32_bf16 v[48:51], v[186:189], v[194:197], v[48:51]
	v_mfma_f32_16x16x32_bf16 v[36:39], v[178:181], v[202:205], v[36:39]
	v_mfma_f32_16x16x32_bf16 v[32:35], v[186:189], v[202:205], v[32:35]
	v_mfma_f32_16x16x32_bf16 v[20:23], v[178:181], v[210:213], v[20:23]
	v_mfma_f32_16x16x32_bf16 v[16:19], v[186:189], v[210:213], v[16:19]
	v_mfma_f32_16x16x32_bf16 v[4:7], v[178:181], v[218:221], v[4:7]
	v_mfma_f32_16x16x32_bf16 v[0:3], v[186:189], v[218:221], v[0:3]
	s_setprio 0
	s_barrier
	s_add_i32 s76, s76, 2
	s_add_u32 s48, s48, 0x100
	s_addc_u32 s49, s49, 0
	s_add_u32 s74, s74, 0x100
	s_addc_u32 s75, s75, 0
	s_cmp_gt_u32 s76, 29
	s_cbranch_scc0 .LBB0_151
	s_and_b64 vcc, exec, s[12:13]
	s_cbranch_vccz .LBB0_154
	s_barrier

.LBB0_260:
	ds_read_b128 v[140:143], v181
	ds_read_b128 v[144:147], v181 offset:1024
	ds_read_b128 v[148:151], v181 offset:2048
	ds_read_b128 v[152:155], v181 offset:3072
	ds_read_b128 v[156:159], v182
	ds_read_b128 v[160:163], v182 offset:1024
	ds_read_b128 v[164:167], v182 offset:2048
	ds_read_b128 v[168:171], v182 offset:3072
	s_add_u32 s64, s50, 0x100
	s_addc_u32 s65, s51, 0
	s_cmpk_eq_i32 s80, 0x54
	s_cselect_b32 s71, s11, s65
	s_cselect_b32 s70, s10, s64
	s_cselect_b32 s69, s49, s79
	s_cselect_b32 s68, s48, s78
	s_add_i32 m0, s4, 0xc000
	ds_read_b128 v[172:175], v183
	ds_read_b128 v[184:187], v183 offset:1024
	ds_read_b128 v[188:191], v183 offset:2048
	ds_read_b128 v[192:195], v183 offset:3072
	ds_read_b128 v[196:199], v183 offset:4096
	ds_read_b128 v[200:203], v183 offset:5120
	ds_read_b128 v[204:207], v183 offset:6144
	ds_read_b128 v[208:211], v183 offset:7168
	global_load_lds_dwordx4 v132, s[50:51]
	s_add_i32 m0, s4, 0xe000
	s_nop 0
	global_load_lds_dwordx4 v134, s[50:51]
	s_waitcnt vmcnt(8)
	s_waitcnt lgkmcnt(0)
	s_barrier
	s_setprio 3
	s_waitcnt lgkmcnt(0)
	v_mfma_f32_16x16x32_bf16 v[124:127], v[140:143], v[172:175], v[124:127]
	v_mfma_f32_16x16x32_bf16 v[120:123], v[148:151], v[172:175], v[120:123]
	v_mfma_f32_16x16x32_bf16 v[108:111], v[140:143], v[188:191], v[108:111]
	v_mfma_f32_16x16x32_bf16 v[104:107], v[148:151], v[188:191], v[104:107]
	v_mfma_f32_16x16x32_bf16 v[92:95], v[140:143], v[196:199], v[92:95]
	v_mfma_f32_16x16x32_bf16 v[88:91], v[148:151], v[196:199], v[88:91]
	v_mfma_f32_16x16x32_bf16 v[76:79], v[140:143], v[204:207], v[76:79]
	v_mfma_f32_16x16x32_bf16 v[72:75], v[148:151], v[204:207], v[72:75]
	v_mfma_f32_16x16x32_bf16 v[124:127], v[144:147], v[184:187], v[124:127]
	v_mfma_f32_16x16x32_bf16 v[120:123], v[152:155], v[184:187], v[120:123]
	v_mfma_f32_16x16x32_bf16 v[108:111], v[144:147], v[192:195], v[108:111]
	v_mfma_f32_16x16x32_bf16 v[104:107], v[152:155], v[192:195], v[104:107]
	v_mfma_f32_16x16x32_bf16 v[92:95], v[144:147], v[200:203], v[92:95]
	v_mfma_f32_16x16x32_bf16 v[88:91], v[152:155], v[200:203], v[88:91]
	v_mfma_f32_16x16x32_bf16 v[76:79], v[144:147], v[208:211], v[76:79]
	v_mfma_f32_16x16x32_bf16 v[72:75], v[152:155], v[208:211], v[72:75]
	s_setprio 0
	s_setprio 3
	v_mfma_f32_16x16x32_bf16 v[116:119], v[156:159], v[172:175], v[116:119]
	v_mfma_f32_16x16x32_bf16 v[112:115], v[164:167], v[172:175], v[112:115]
	v_mfma_f32_16x16x32_bf16 v[100:103], v[156:159], v[188:191], v[100:103]
	v_mfma_f32_16x16x32_bf16 v[96:99], v[164:167], v[188:191], v[96:99]
	v_mfma_f32_16x16x32_bf16 v[84:87], v[156:159], v[196:199], v[84:87]
	v_mfma_f32_16x16x32_bf16 v[80:83], v[164:167], v[196:199], v[80:83]
	v_mfma_f32_16x16x32_bf16 v[68:71], v[156:159], v[204:207], v[68:71]
	v_mfma_f32_16x16x32_bf16 v[64:67], v[164:167], v[204:207], v[64:67]
	v_mfma_f32_16x16x32_bf16 v[116:119], v[160:163], v[184:187], v[116:119]
	v_mfma_f32_16x16x32_bf16 v[112:115], v[168:171], v[184:187], v[112:115]
	v_mfma_f32_16x16x32_bf16 v[100:103], v[160:163], v[192:195], v[100:103]
	v_mfma_f32_16x16x32_bf16 v[96:99], v[168:171], v[192:195], v[96:99]
	v_mfma_f32_16x16x32_bf16 v[84:87], v[160:163], v[200:203], v[84:87]
	v_mfma_f32_16x16x32_bf16 v[80:83], v[168:171], v[200:203], v[80:83]
	v_mfma_f32_16x16x32_bf16 v[68:71], v[160:163], v[208:211], v[68:71]
	v_mfma_f32_16x16x32_bf16 v[64:67], v[168:171], v[208:211], v[64:67]
	s_setprio 0
	s_barrier
	s_add_u32 s98, s68, s16
	s_addc_u32 s99, s69, s17
	s_add_u32 s100, s70, s16
	s_addc_u32 s101, s71, s17
	s_add_i32 s50, s72, s89
	s_mov_b32 m0, s50
	ds_read_b128 v[172:175], v183 offset:16384
	ds_read_b128 v[184:187], v183 offset:17408
	ds_read_b128 v[188:191], v183 offset:18432
	ds_read_b128 v[192:195], v183 offset:19456
	ds_read_b128 v[196:199], v183 offset:20480
	ds_read_b128 v[200:203], v183 offset:21504
	ds_read_b128 v[204:207], v183 offset:22528
	ds_read_b128 v[208:211], v183 offset:23552
	global_load_lds_dwordx4 v128, s[68:69]
	s_add_i32 m0, s50, 0x2000
	s_add_u32 s50, s68, 0x160000
	s_addc_u32 s51, s69, 0
	s_add_i32 s81, s73, s89
	global_load_lds_dwordx4 v130, s[68:69]
	s_mov_b32 m0, s81
	s_nop 0
	global_load_lds_dwordx4 v128, s[50:51]
	s_add_i32 m0, s81, 0x2000
	s_nop 0
	global_load_lds_dwordx4 v130, s[50:51]
	s_mov_b32 m0, s4
	s_nop 0
	global_load_lds_dwordx4 v128, s[70:71]
	s_mov_b32 m0, s5
	s_nop 0
	global_load_lds_dwordx4 v130, s[70:71]
	s_waitcnt vmcnt(8)
	s_waitcnt lgkmcnt(0)
	s_barrier
	s_setprio 3
	s_waitcnt lgkmcnt(0)
	v_mfma_f32_16x16x32_bf16 v[60:63], v[140:143], v[172:175], v[60:63]
	v_mfma_f32_16x16x32_bf16 v[56:59], v[148:151], v[172:175], v[56:59]
	v_mfma_f32_16x16x32_bf16 v[44:47], v[140:143], v[188:191], v[44:47]
	v_mfma_f32_16x16x32_bf16 v[40:43], v[148:151], v[188:191], v[40:43]
	v_mfma_f32_16x16x32_bf16 v[28:31], v[140:143], v[196:199], v[28:31]
	v_mfma_f32_16x16x32_bf16 v[24:27], v[148:151], v[196:199], v[24:27]
	v_mfma_f32_16x16x32_bf16 v[12:15], v[140:143], v[204:207], v[12:15]
	v_mfma_f32_16x16x32_bf16 v[8:11], v[148:151], v[204:207], v[8:11]
	v_mfma_f32_16x16x32_bf16 v[60:63], v[144:147], v[184:187], v[60:63]
	v_mfma_f32_16x16x32_bf16 v[56:59], v[152:155], v[184:187], v[56:59]
	v_mfma_f32_16x16x32_bf16 v[44:47], v[144:147], v[192:195], v[44:47]
	v_mfma_f32_16x16x32_bf16 v[40:43], v[152:155], v[192:195], v[40:43]
	v_mfma_f32_16x16x32_bf16 v[28:31], v[144:147], v[200:203], v[28:31]
	v_mfma_f32_16x16x32_bf16 v[24:27], v[152:155], v[200:203], v[24:27]
	v_mfma_f32_16x16x32_bf16 v[12:15], v[144:147], v[208:211], v[12:15]
	v_mfma_f32_16x16x32_bf16 v[8:11], v[152:155], v[208:211], v[8:11]
	s_setprio 0
	s_setprio 3
	v_mfma_f32_16x16x32_bf16 v[52:55], v[156:159], v[172:175], v[52:55]
	v_mfma_f32_16x16x32_bf16 v[48:51], v[164:167], v[172:175], v[48:51]
	v_mfma_f32_16x16x32_bf16 v[36:39], v[156:159], v[188:191], v[36:39]
	v_mfma_f32_16x16x32_bf16 v[32:35], v[164:167], v[188:191], v[32:35]
	v_mfma_f32_16x16x32_bf16 v[20:23], v[156:159], v[196:199], v[20:23]
	v_mfma_f32_16x16x32_bf16 v[16:19], v[164:167], v[196:199], v[16:19]
	v_mfma_f32_16x16x32_bf16 v[4:7], v[156:159], v[204:207], v[4:7]
	v_mfma_f32_16x16x32_bf16 v[0:3], v[164:167], v[204:207], v[0:3]
	v_mfma_f32_16x16x32_bf16 v[52:55], v[160:163], v[184:187], v[52:55]
	v_mfma_f32_16x16x32_bf16 v[48:51], v[168:171], v[184:187], v[48:51]
	v_mfma_f32_16x16x32_bf16 v[36:39], v[160:163], v[192:195], v[36:39]
	v_mfma_f32_16x16x32_bf16 v[32:35], v[168:171], v[192:195], v[32:35]
	v_mfma_f32_16x16x32_bf16 v[20:23], v[160:163], v[200:203], v[20:23]
	v_mfma_f32_16x16x32_bf16 v[16:19], v[168:171], v[200:203], v[16:19]
	v_mfma_f32_16x16x32_bf16 v[4:7], v[160:163], v[208:211], v[4:7]
	v_mfma_f32_16x16x32_bf16 v[0:3], v[168:171], v[208:211], v[0:3]
	s_setprio 0
	s_barrier
	s_add_i32 s81, 0, 0x18000
	s_add_i32 s82, 0, 0x1c000
	v_add_u32_e32 v152, s81, v177
	v_add_u32_e32 v168, s82, v177
	ds_read_b128 v[140:143], v152
	ds_read_b128 v[144:147], v152 offset:1024
	ds_read_b128 v[148:151], v152 offset:2048
	ds_read_b128 v[152:155], v152 offset:3072
	ds_read_b128 v[156:159], v168
	ds_read_b128 v[160:163], v168 offset:1024
	ds_read_b128 v[164:167], v168 offset:2048
	ds_read_b128 v[168:171], v168 offset:3072
	s_add_u32 s50, s70, 0x160000
	s_addc_u32 s51, s71, 0
	s_mov_b32 m0, s28
	ds_read_b128 v[172:175], v183 offset:32768
	ds_read_b128 v[184:187], v183 offset:33792
	ds_read_b128 v[188:191], v183 offset:34816
	ds_read_b128 v[192:195], v183 offset:35840
	ds_read_b128 v[196:199], v183 offset:36864
	ds_read_b128 v[200:203], v183 offset:37888
	ds_read_b128 v[204:207], v183 offset:38912
	ds_read_b128 v[208:211], v183 offset:39936
	global_load_lds_dwordx4 v128, s[50:51]
	s_mov_b32 m0, s29
	s_nop 0
	global_load_lds_dwordx4 v130, s[50:51]
	s_waitcnt vmcnt(8)
	s_waitcnt lgkmcnt(0)
	s_barrier
	s_setprio 3
	s_waitcnt lgkmcnt(0)
	v_mfma_f32_16x16x32_bf16 v[124:127], v[140:143], v[172:175], v[124:127]
	v_mfma_f32_16x16x32_bf16 v[120:123], v[148:151], v[172:175], v[120:123]
	v_mfma_f32_16x16x32_bf16 v[108:111], v[140:143], v[188:191], v[108:111]
	v_mfma_f32_16x16x32_bf16 v[104:107], v[148:151], v[188:191], v[104:107]
	v_mfma_f32_16x16x32_bf16 v[92:95], v[140:143], v[196:199], v[92:95]
	v_mfma_f32_16x16x32_bf16 v[88:91], v[148:151], v[196:199], v[88:91]
	v_mfma_f32_16x16x32_bf16 v[76:79], v[140:143], v[204:207], v[76:79]
	v_mfma_f32_16x16x32_bf16 v[72:75], v[148:151], v[204:207], v[72:75]
	v_mfma_f32_16x16x32_bf16 v[124:127], v[144:147], v[184:187], v[124:127]
	v_mfma_f32_16x16x32_bf16 v[120:123], v[152:155], v[184:187], v[120:123]
	v_mfma_f32_16x16x32_bf16 v[108:111], v[144:147], v[192:195], v[108:111]
	v_mfma_f32_16x16x32_bf16 v[104:107], v[152:155], v[192:195], v[104:107]
	v_mfma_f32_16x16x32_bf16 v[92:95], v[144:147], v[200:203], v[92:95]
	v_mfma_f32_16x16x32_bf16 v[88:91], v[152:155], v[200:203], v[88:91]
	v_mfma_f32_16x16x32_bf16 v[76:79], v[144:147], v[208:211], v[76:79]
	v_mfma_f32_16x16x32_bf16 v[72:75], v[152:155], v[208:211], v[72:75]
	s_setprio 0
	s_setprio 3
	v_mfma_f32_16x16x32_bf16 v[116:119], v[156:159], v[172:175], v[116:119]
	v_mfma_f32_16x16x32_bf16 v[112:115], v[164:167], v[172:175], v[112:115]
	v_mfma_f32_16x16x32_bf16 v[100:103], v[156:159], v[188:191], v[100:103]
	v_mfma_f32_16x16x32_bf16 v[96:99], v[164:167], v[188:191], v[96:99]
	v_mfma_f32_16x16x32_bf16 v[84:87], v[156:159], v[196:199], v[84:87]
	v_mfma_f32_16x16x32_bf16 v[80:83], v[164:167], v[196:199], v[80:83]
	v_mfma_f32_16x16x32_bf16 v[68:71], v[156:159], v[204:207], v[68:71]
	v_mfma_f32_16x16x32_bf16 v[64:67], v[164:167], v[204:207], v[64:67]
	v_mfma_f32_16x16x32_bf16 v[116:119], v[160:163], v[184:187], v[116:119]
	v_mfma_f32_16x16x32_bf16 v[112:115], v[168:171], v[184:187], v[112:115]
	v_mfma_f32_16x16x32_bf16 v[100:103], v[160:163], v[192:195], v[100:103]
	v_mfma_f32_16x16x32_bf16 v[96:99], v[168:171], v[192:195], v[96:99]
	v_mfma_f32_16x16x32_bf16 v[84:87], v[160:163], v[200:203], v[84:87]
	v_mfma_f32_16x16x32_bf16 v[80:83], v[168:171], v[200:203], v[80:83]
	v_mfma_f32_16x16x32_bf16 v[68:71], v[160:163], v[208:211], v[68:71]
	v_mfma_f32_16x16x32_bf16 v[64:67], v[168:171], v[208:211], v[64:67]
	s_setprio 0
	s_barrier
	s_add_i32 s50, s81, s89
	s_mov_b32 m0, s50
	ds_read_b128 v[172:175], v183 offset:49152
	ds_read_b128 v[184:187], v183 offset:50176
	ds_read_b128 v[188:191], v183 offset:51200
	ds_read_b128 v[192:195], v183 offset:52224
	ds_read_b128 v[196:199], v183 offset:53248
	ds_read_b128 v[200:203], v183 offset:54272
	ds_read_b128 v[204:207], v183 offset:55296
	ds_read_b128 v[208:211], v183 offset:56320
	global_load_lds_dwordx4 v128, s[98:99]
	s_add_i32 m0, s50, 0x2000
	s_add_u32 s50, s68, 0x160080
	s_addc_u32 s51, s69, 0
	s_add_i32 s68, s82, s89
	global_load_lds_dwordx4 v130, s[98:99]
	s_mov_b32 m0, s68
	s_nop 0
	global_load_lds_dwordx4 v128, s[50:51]
	s_add_i32 m0, s68, 0x2000
	s_nop 0
	global_load_lds_dwordx4 v130, s[50:51]
	s_mov_b32 m0, s57
	s_nop 0
	global_load_lds_dwordx4 v128, s[100:101]
	s_mov_b32 m0, s58
	s_nop 0
	global_load_lds_dwordx4 v130, s[100:101]
	s_waitcnt vmcnt(8)
	s_waitcnt lgkmcnt(0)
	s_barrier
	s_setprio 3
	s_waitcnt lgkmcnt(0)
	v_mfma_f32_16x16x32_bf16 v[60:63], v[140:143], v[172:175], v[60:63]
	v_mfma_f32_16x16x32_bf16 v[56:59], v[148:151], v[172:175], v[56:59]
	v_mfma_f32_16x16x32_bf16 v[44:47], v[140:143], v[188:191], v[44:47]
	v_mfma_f32_16x16x32_bf16 v[40:43], v[148:151], v[188:191], v[40:43]
	v_mfma_f32_16x16x32_bf16 v[28:31], v[140:143], v[196:199], v[28:31]
	v_mfma_f32_16x16x32_bf16 v[24:27], v[148:151], v[196:199], v[24:27]
	v_mfma_f32_16x16x32_bf16 v[12:15], v[140:143], v[204:207], v[12:15]
	v_mfma_f32_16x16x32_bf16 v[8:11], v[148:151], v[204:207], v[8:11]
	v_mfma_f32_16x16x32_bf16 v[60:63], v[144:147], v[184:187], v[60:63]
	v_mfma_f32_16x16x32_bf16 v[56:59], v[152:155], v[184:187], v[56:59]
	v_mfma_f32_16x16x32_bf16 v[44:47], v[144:147], v[192:195], v[44:47]
	v_mfma_f32_16x16x32_bf16 v[40:43], v[152:155], v[192:195], v[40:43]
	v_mfma_f32_16x16x32_bf16 v[28:31], v[144:147], v[200:203], v[28:31]
	v_mfma_f32_16x16x32_bf16 v[24:27], v[152:155], v[200:203], v[24:27]
	v_mfma_f32_16x16x32_bf16 v[12:15], v[144:147], v[208:211], v[12:15]
	v_mfma_f32_16x16x32_bf16 v[8:11], v[152:155], v[208:211], v[8:11]
	s_setprio 0
	s_setprio 3
	v_mfma_f32_16x16x32_bf16 v[52:55], v[156:159], v[172:175], v[52:55]
	v_mfma_f32_16x16x32_bf16 v[48:51], v[164:167], v[172:175], v[48:51]
	v_mfma_f32_16x16x32_bf16 v[36:39], v[156:159], v[188:191], v[36:39]
	v_mfma_f32_16x16x32_bf16 v[32:35], v[164:167], v[188:191], v[32:35]
	v_mfma_f32_16x16x32_bf16 v[20:23], v[156:159], v[196:199], v[20:23]
	v_mfma_f32_16x16x32_bf16 v[16:19], v[164:167], v[196:199], v[16:19]
	v_mfma_f32_16x16x32_bf16 v[4:7], v[156:159], v[204:207], v[4:7]
	v_mfma_f32_16x16x32_bf16 v[0:3], v[164:167], v[204:207], v[0:3]
	v_mfma_f32_16x16x32_bf16 v[52:55], v[160:163], v[184:187], v[52:55]
	v_mfma_f32_16x16x32_bf16 v[48:51], v[168:171], v[184:187], v[48:51]
	v_mfma_f32_16x16x32_bf16 v[36:39], v[160:163], v[192:195], v[36:39]
	v_mfma_f32_16x16x32_bf16 v[32:35], v[168:171], v[192:195], v[32:35]
	v_mfma_f32_16x16x32_bf16 v[20:23], v[160:163], v[200:203], v[20:23]
	v_mfma_f32_16x16x32_bf16 v[16:19], v[168:171], v[200:203], v[16:19]
	v_mfma_f32_16x16x32_bf16 v[4:7], v[160:163], v[208:211], v[4:7]
	v_mfma_f32_16x16x32_bf16 v[0:3], v[168:171], v[208:211], v[0:3]
	s_setprio 0
	s_barrier
	s_add_i32 s80, s80, 2
	s_add_u32 s78, s78, 0x100
	s_addc_u32 s79, s79, 0
	s_cmpk_gt_u32 s80, 0x55
	s_mov_b64 s[50:51], s[64:65]
	s_cbranch_scc0 .LBB0_260
	s_and_b64 vcc, exec, s[18:19]
	s_cbranch_vccz .LBB0_263
	s_barrier

.LBB0_348:
	ds_read_b128 v[128:131], v243
	ds_read_b128 v[132:135], v243 offset:1024
	ds_read_b128 v[136:139], v243 offset:2048
	ds_read_b128 v[140:143], v243 offset:3072
	ds_read_b128 v[158:161], v244
	ds_read_b128 v[162:165], v244 offset:1024
	ds_read_b128 v[166:169], v244 offset:2048
	ds_read_b128 v[170:173], v244 offset:3072
	s_add_u32 s18, s16, 0xfff80080
	s_addc_u32 s19, s17, -1
	s_cmp_eq_u32 s77, 28
	s_cselect_b32 s21, s15, s19
	s_cselect_b32 s20, s29, s18
	s_cselect_b32 s19, s46, s76
	s_cselect_b32 s18, s51, s69
	s_add_i32 m0, s63, 0xc000
	ds_read_b128 v[174:177], v245
	ds_read_b128 v[178:181], v245 offset:1024
	ds_read_b128 v[182:185], v245 offset:2048
	ds_read_b128 v[186:189], v245 offset:3072
	ds_read_b128 v[190:193], v245 offset:4096
	ds_read_b128 v[194:197], v245 offset:5120
	ds_read_b128 v[198:201], v245 offset:6144
	ds_read_b128 v[202:205], v245 offset:7168
	global_load_lds_dwordx4 v150, s[16:17]
	s_add_i32 m0, s63, 0xe000
	s_nop 0
	global_load_lds_dwordx4 v152, s[16:17]
	s_waitcnt vmcnt(8)
	s_waitcnt lgkmcnt(0)
	s_barrier
	s_setprio 3
	s_waitcnt lgkmcnt(0)
	v_mfma_f32_16x16x32_bf16 v[124:127], v[128:131], v[174:177], v[124:127]
	v_mfma_f32_16x16x32_bf16 v[120:123], v[136:139], v[174:177], v[120:123]
	v_mfma_f32_16x16x32_bf16 v[116:119], v[128:131], v[182:185], v[116:119]
	v_mfma_f32_16x16x32_bf16 v[112:115], v[136:139], v[182:185], v[112:115]
	v_mfma_f32_16x16x32_bf16 v[100:103], v[128:131], v[190:193], v[100:103]
	v_mfma_f32_16x16x32_bf16 v[96:99], v[136:139], v[190:193], v[96:99]
	v_mfma_f32_16x16x32_bf16 v[84:87], v[128:131], v[198:201], v[84:87]
	v_mfma_f32_16x16x32_bf16 v[80:83], v[136:139], v[198:201], v[80:83]
	v_mfma_f32_16x16x32_bf16 v[124:127], v[132:135], v[178:181], v[124:127]
	v_mfma_f32_16x16x32_bf16 v[120:123], v[140:143], v[178:181], v[120:123]
	v_mfma_f32_16x16x32_bf16 v[116:119], v[132:135], v[186:189], v[116:119]
	v_mfma_f32_16x16x32_bf16 v[112:115], v[140:143], v[186:189], v[112:115]
	v_mfma_f32_16x16x32_bf16 v[100:103], v[132:135], v[194:197], v[100:103]
	v_mfma_f32_16x16x32_bf16 v[96:99], v[140:143], v[194:197], v[96:99]
	v_mfma_f32_16x16x32_bf16 v[84:87], v[132:135], v[202:205], v[84:87]
	v_mfma_f32_16x16x32_bf16 v[80:83], v[140:143], v[202:205], v[80:83]
	s_setprio 0
	s_setprio 3
	v_mfma_f32_16x16x32_bf16 v[108:111], v[158:161], v[174:177], v[108:111]
	v_mfma_f32_16x16x32_bf16 v[104:107], v[166:169], v[174:177], v[104:107]
	v_mfma_f32_16x16x32_bf16 v[92:95], v[158:161], v[182:185], v[92:95]
	v_mfma_f32_16x16x32_bf16 v[88:91], v[166:169], v[182:185], v[88:91]
	v_mfma_f32_16x16x32_bf16 v[76:79], v[158:161], v[190:193], v[76:79]
	v_mfma_f32_16x16x32_bf16 v[72:75], v[166:169], v[190:193], v[72:75]
	v_mfma_f32_16x16x32_bf16 v[68:71], v[158:161], v[198:201], v[68:71]
	v_mfma_f32_16x16x32_bf16 v[64:67], v[166:169], v[198:201], v[64:67]
	v_mfma_f32_16x16x32_bf16 v[108:111], v[162:165], v[178:181], v[108:111]
	v_mfma_f32_16x16x32_bf16 v[104:107], v[170:173], v[178:181], v[104:107]
	v_mfma_f32_16x16x32_bf16 v[92:95], v[162:165], v[186:189], v[92:95]
	v_mfma_f32_16x16x32_bf16 v[88:91], v[170:173], v[186:189], v[88:91]
	v_mfma_f32_16x16x32_bf16 v[76:79], v[162:165], v[194:197], v[76:79]
	v_mfma_f32_16x16x32_bf16 v[72:75], v[170:173], v[194:197], v[72:75]
	v_mfma_f32_16x16x32_bf16 v[68:71], v[162:165], v[202:205], v[68:71]
	v_mfma_f32_16x16x32_bf16 v[64:67], v[170:173], v[202:205], v[64:67]
	s_setprio 0
	s_barrier
	s_add_u32 s98, s18, s48
	s_addc_u32 s99, s19, s49
	s_add_u32 s100, s20, s48
	s_addc_u32 s101, s21, s49
	s_add_i32 s78, s93, s89
	s_mov_b32 m0, s78
	ds_read_b128 v[174:177], v245 offset:16384
	ds_read_b128 v[178:181], v245 offset:17408
	ds_read_b128 v[182:185], v245 offset:18432
	ds_read_b128 v[186:189], v245 offset:19456
	ds_read_b128 v[190:193], v245 offset:20480
	ds_read_b128 v[194:197], v245 offset:21504
	ds_read_b128 v[198:201], v245 offset:22528
	ds_read_b128 v[202:205], v245 offset:23552
	global_load_lds_dwordx4 v144, s[18:19]
	s_add_i32 m0, s78, 0x2000
	s_add_u32 s78, s18, 0x80000
	s_addc_u32 s79, s19, 0
	s_add_i32 vcc_lo, s91, s89
	global_load_lds_dwordx4 v146, s[18:19]
	s_mov_b32 m0, vcc_lo
	s_nop 0
	global_load_lds_dwordx4 v144, s[78:79]
	s_add_i32 m0, vcc_lo, 0x2000
	s_nop 0
	global_load_lds_dwordx4 v146, s[78:79]
	s_mov_b32 m0, s63
	s_nop 0
	global_load_lds_dwordx4 v144, s[20:21]
	s_mov_b32 m0, s71
	s_nop 0
	global_load_lds_dwordx4 v146, s[20:21]
	s_waitcnt vmcnt(8)
	s_waitcnt lgkmcnt(0)
	s_barrier
	s_setprio 3
	s_waitcnt lgkmcnt(0)
	v_mfma_f32_16x16x32_bf16 v[60:63], v[128:131], v[174:177], v[60:63]
	v_mfma_f32_16x16x32_bf16 v[56:59], v[136:139], v[174:177], v[56:59]
	v_mfma_f32_16x16x32_bf16 v[52:55], v[128:131], v[182:185], v[52:55]
	v_mfma_f32_16x16x32_bf16 v[48:51], v[136:139], v[182:185], v[48:51]
	v_mfma_f32_16x16x32_bf16 v[36:39], v[128:131], v[190:193], v[36:39]
	v_mfma_f32_16x16x32_bf16 v[32:35], v[136:139], v[190:193], v[32:35]
	v_mfma_f32_16x16x32_bf16 v[20:23], v[128:131], v[198:201], v[20:23]
	v_mfma_f32_16x16x32_bf16 v[16:19], v[136:139], v[198:201], v[16:19]
	v_mfma_f32_16x16x32_bf16 v[60:63], v[132:135], v[178:181], v[60:63]
	v_mfma_f32_16x16x32_bf16 v[56:59], v[140:143], v[178:181], v[56:59]
	v_mfma_f32_16x16x32_bf16 v[52:55], v[132:135], v[186:189], v[52:55]
	v_mfma_f32_16x16x32_bf16 v[48:51], v[140:143], v[186:189], v[48:51]
	v_mfma_f32_16x16x32_bf16 v[36:39], v[132:135], v[194:197], v[36:39]
	v_mfma_f32_16x16x32_bf16 v[32:35], v[140:143], v[194:197], v[32:35]
	v_mfma_f32_16x16x32_bf16 v[20:23], v[132:135], v[202:205], v[20:23]
	v_mfma_f32_16x16x32_bf16 v[16:19], v[140:143], v[202:205], v[16:19]
	s_setprio 0
	s_setprio 3
	v_mfma_f32_16x16x32_bf16 v[44:47], v[158:161], v[174:177], v[44:47]
	v_mfma_f32_16x16x32_bf16 v[40:43], v[166:169], v[174:177], v[40:43]
	v_mfma_f32_16x16x32_bf16 v[28:31], v[158:161], v[182:185], v[28:31]
	v_mfma_f32_16x16x32_bf16 v[24:27], v[166:169], v[182:185], v[24:27]
	v_mfma_f32_16x16x32_bf16 v[12:15], v[158:161], v[190:193], v[12:15]
	v_mfma_f32_16x16x32_bf16 v[8:11], v[166:169], v[190:193], v[8:11]
	v_mfma_f32_16x16x32_bf16 v[4:7], v[158:161], v[198:201], v[4:7]
	v_mfma_f32_16x16x32_bf16 v[0:3], v[166:169], v[198:201], v[0:3]
	v_mfma_f32_16x16x32_bf16 v[44:47], v[162:165], v[178:181], v[44:47]
	v_mfma_f32_16x16x32_bf16 v[40:43], v[170:173], v[178:181], v[40:43]
	v_mfma_f32_16x16x32_bf16 v[28:31], v[162:165], v[186:189], v[28:31]
	v_mfma_f32_16x16x32_bf16 v[24:27], v[170:173], v[186:189], v[24:27]
	v_mfma_f32_16x16x32_bf16 v[12:15], v[162:165], v[194:197], v[12:15]
	v_mfma_f32_16x16x32_bf16 v[8:11], v[170:173], v[194:197], v[8:11]
	v_mfma_f32_16x16x32_bf16 v[4:7], v[162:165], v[202:205], v[4:7]
	v_mfma_f32_16x16x32_bf16 v[0:3], v[170:173], v[202:205], v[0:3]
	s_setprio 0
	s_barrier
	s_add_i32 s78, 0, 0x18000
	s_add_i32 s79, 0, 0x1c000
	v_add_u32_e32 v140, s78, v242
	v_add_u32_e32 v148, s79, v242
	ds_read_b128 v[128:131], v140
	ds_read_b128 v[132:135], v140 offset:1024
	ds_read_b128 v[136:139], v140 offset:2048
	ds_read_b128 v[140:143], v140 offset:3072
	ds_read_b128 v[158:161], v148
	ds_read_b128 v[162:165], v148 offset:1024
	ds_read_b128 v[166:169], v148 offset:2048
	ds_read_b128 v[170:173], v148 offset:3072
	s_add_u32 s20, s20, 0x80000
	s_addc_u32 s21, s21, 0
	s_mov_b32 m0, s80
	ds_read_b128 v[174:177], v245 offset:32768
	ds_read_b128 v[178:181], v245 offset:33792
	ds_read_b128 v[182:185], v245 offset:34816
	ds_read_b128 v[186:189], v245 offset:35840
	ds_read_b128 v[190:193], v245 offset:36864
	ds_read_b128 v[194:197], v245 offset:37888
	ds_read_b128 v[198:201], v245 offset:38912
	ds_read_b128 v[202:205], v245 offset:39936
	global_load_lds_dwordx4 v144, s[20:21]
	s_mov_b32 m0, s81
	s_nop 0
	global_load_lds_dwordx4 v146, s[20:21]
	s_waitcnt vmcnt(8)
	s_waitcnt lgkmcnt(0)
	s_barrier
	s_setprio 3
	s_waitcnt lgkmcnt(0)
	v_mfma_f32_16x16x32_bf16 v[124:127], v[128:131], v[174:177], v[124:127]
	v_mfma_f32_16x16x32_bf16 v[120:123], v[136:139], v[174:177], v[120:123]
	v_mfma_f32_16x16x32_bf16 v[116:119], v[128:131], v[182:185], v[116:119]
	v_mfma_f32_16x16x32_bf16 v[112:115], v[136:139], v[182:185], v[112:115]
	v_mfma_f32_16x16x32_bf16 v[100:103], v[128:131], v[190:193], v[100:103]
	v_mfma_f32_16x16x32_bf16 v[96:99], v[136:139], v[190:193], v[96:99]
	v_mfma_f32_16x16x32_bf16 v[84:87], v[128:131], v[198:201], v[84:87]
	v_mfma_f32_16x16x32_bf16 v[80:83], v[136:139], v[198:201], v[80:83]
	v_mfma_f32_16x16x32_bf16 v[124:127], v[132:135], v[178:181], v[124:127]
	v_mfma_f32_16x16x32_bf16 v[120:123], v[140:143], v[178:181], v[120:123]
	v_mfma_f32_16x16x32_bf16 v[116:119], v[132:135], v[186:189], v[116:119]
	v_mfma_f32_16x16x32_bf16 v[112:115], v[140:143], v[186:189], v[112:115]
	v_mfma_f32_16x16x32_bf16 v[100:103], v[132:135], v[194:197], v[100:103]
	v_mfma_f32_16x16x32_bf16 v[96:99], v[140:143], v[194:197], v[96:99]
	v_mfma_f32_16x16x32_bf16 v[84:87], v[132:135], v[202:205], v[84:87]
	v_mfma_f32_16x16x32_bf16 v[80:83], v[140:143], v[202:205], v[80:83]
	s_setprio 0
	s_setprio 3
	v_mfma_f32_16x16x32_bf16 v[108:111], v[158:161], v[174:177], v[108:111]
	v_mfma_f32_16x16x32_bf16 v[104:107], v[166:169], v[174:177], v[104:107]
	v_mfma_f32_16x16x32_bf16 v[92:95], v[158:161], v[182:185], v[92:95]
	v_mfma_f32_16x16x32_bf16 v[88:91], v[166:169], v[182:185], v[88:91]
	v_mfma_f32_16x16x32_bf16 v[76:79], v[158:161], v[190:193], v[76:79]
	v_mfma_f32_16x16x32_bf16 v[72:75], v[166:169], v[190:193], v[72:75]
	v_mfma_f32_16x16x32_bf16 v[68:71], v[158:161], v[198:201], v[68:71]
	v_mfma_f32_16x16x32_bf16 v[64:67], v[166:169], v[198:201], v[64:67]
	v_mfma_f32_16x16x32_bf16 v[108:111], v[162:165], v[178:181], v[108:111]
	v_mfma_f32_16x16x32_bf16 v[104:107], v[170:173], v[178:181], v[104:107]
	v_mfma_f32_16x16x32_bf16 v[92:95], v[162:165], v[186:189], v[92:95]
	v_mfma_f32_16x16x32_bf16 v[88:91], v[170:173], v[186:189], v[88:91]
	v_mfma_f32_16x16x32_bf16 v[76:79], v[162:165], v[194:197], v[76:79]
	v_mfma_f32_16x16x32_bf16 v[72:75], v[170:173], v[194:197], v[72:75]
	v_mfma_f32_16x16x32_bf16 v[68:71], v[162:165], v[202:205], v[68:71]
	v_mfma_f32_16x16x32_bf16 v[64:67], v[170:173], v[202:205], v[64:67]
	s_setprio 0
	s_barrier
	s_add_i32 s20, s78, s89
	s_mov_b32 m0, s20
	ds_read_b128 v[174:177], v245 offset:49152
	ds_read_b128 v[178:181], v245 offset:50176
	ds_read_b128 v[182:185], v245 offset:51200
	ds_read_b128 v[186:189], v245 offset:52224
	ds_read_b128 v[190:193], v245 offset:53248
	ds_read_b128 v[194:197], v245 offset:54272
	ds_read_b128 v[198:201], v245 offset:55296
	ds_read_b128 v[202:205], v245 offset:56320
	global_load_lds_dwordx4 v144, s[98:99]
	s_add_i32 m0, s20, 0x2000
	s_add_u32 s18, s18, 0x80080
	s_addc_u32 s19, s19, 0
	s_add_i32 s20, s79, s89
	global_load_lds_dwordx4 v146, s[98:99]
	s_mov_b32 m0, s20
	s_nop 0
	global_load_lds_dwordx4 v144, s[18:19]
	s_add_i32 m0, s20, 0x2000
	s_nop 0
	global_load_lds_dwordx4 v146, s[18:19]
	s_mov_b32 m0, s92
	s_nop 0
	global_load_lds_dwordx4 v144, s[100:101]
	s_mov_b32 m0, s88
	s_nop 0
	global_load_lds_dwordx4 v146, s[100:101]
	s_waitcnt vmcnt(8)
	s_waitcnt lgkmcnt(0)
	s_barrier
	s_setprio 3
	s_waitcnt lgkmcnt(0)
	v_mfma_f32_16x16x32_bf16 v[60:63], v[128:131], v[174:177], v[60:63]
	v_mfma_f32_16x16x32_bf16 v[56:59], v[136:139], v[174:177], v[56:59]
	v_mfma_f32_16x16x32_bf16 v[52:55], v[128:131], v[182:185], v[52:55]
	v_mfma_f32_16x16x32_bf16 v[48:51], v[136:139], v[182:185], v[48:51]
	v_mfma_f32_16x16x32_bf16 v[36:39], v[128:131], v[190:193], v[36:39]
	v_mfma_f32_16x16x32_bf16 v[32:35], v[136:139], v[190:193], v[32:35]
	v_mfma_f32_16x16x32_bf16 v[20:23], v[128:131], v[198:201], v[20:23]
	v_mfma_f32_16x16x32_bf16 v[16:19], v[136:139], v[198:201], v[16:19]
	v_mfma_f32_16x16x32_bf16 v[60:63], v[132:135], v[178:181], v[60:63]
	v_mfma_f32_16x16x32_bf16 v[56:59], v[140:143], v[178:181], v[56:59]
	v_mfma_f32_16x16x32_bf16 v[52:55], v[132:135], v[186:189], v[52:55]
	v_mfma_f32_16x16x32_bf16 v[48:51], v[140:143], v[186:189], v[48:51]
	v_mfma_f32_16x16x32_bf16 v[36:39], v[132:135], v[194:197], v[36:39]
	v_mfma_f32_16x16x32_bf16 v[32:35], v[140:143], v[194:197], v[32:35]
	v_mfma_f32_16x16x32_bf16 v[20:23], v[132:135], v[202:205], v[20:23]
	v_mfma_f32_16x16x32_bf16 v[16:19], v[140:143], v[202:205], v[16:19]
	s_setprio 0
	s_setprio 3
	v_mfma_f32_16x16x32_bf16 v[44:47], v[158:161], v[174:177], v[44:47]
	v_mfma_f32_16x16x32_bf16 v[40:43], v[166:169], v[174:177], v[40:43]
	v_mfma_f32_16x16x32_bf16 v[28:31], v[158:161], v[182:185], v[28:31]
	v_mfma_f32_16x16x32_bf16 v[24:27], v[166:169], v[182:185], v[24:27]
	v_mfma_f32_16x16x32_bf16 v[12:15], v[158:161], v[190:193], v[12:15]
	v_mfma_f32_16x16x32_bf16 v[8:11], v[166:169], v[190:193], v[8:11]
	v_mfma_f32_16x16x32_bf16 v[4:7], v[158:161], v[198:201], v[4:7]
	v_mfma_f32_16x16x32_bf16 v[0:3], v[166:169], v[198:201], v[0:3]
	v_mfma_f32_16x16x32_bf16 v[44:47], v[162:165], v[178:181], v[44:47]
	v_mfma_f32_16x16x32_bf16 v[40:43], v[170:173], v[178:181], v[40:43]
	v_mfma_f32_16x16x32_bf16 v[28:31], v[162:165], v[186:189], v[28:31]
	v_mfma_f32_16x16x32_bf16 v[24:27], v[170:173], v[186:189], v[24:27]
	v_mfma_f32_16x16x32_bf16 v[12:15], v[162:165], v[194:197], v[12:15]
	v_mfma_f32_16x16x32_bf16 v[8:11], v[170:173], v[194:197], v[8:11]
	v_mfma_f32_16x16x32_bf16 v[4:7], v[162:165], v[202:205], v[4:7]
	v_mfma_f32_16x16x32_bf16 v[0:3], v[170:173], v[202:205], v[0:3]
	s_setprio 0
	s_barrier
	s_add_i32 s77, s77, 2
	s_add_u32 s16, s16, 0x100
	s_addc_u32 s17, s17, 0
	s_add_u32 s69, s69, 0x100
	s_addc_u32 s76, s76, 0
	s_cmp_gt_u32 s77, 29
	s_cbranch_scc0 .LBB0_348
	s_and_b64 vcc, exec, s[64:65]
	s_cbranch_vccz .LBB0_351
	s_barrier

.LBB0_750:
	ds_read_b128 v[140:143], v187
	ds_read_b128 v[144:147], v187 offset:1024
	ds_read_b128 v[148:151], v187 offset:2048
	ds_read_b128 v[152:155], v187 offset:3072
	ds_read_b128 v[156:159], v188
	ds_read_b128 v[160:163], v188 offset:1024
	ds_read_b128 v[164:167], v188 offset:2048
	ds_read_b128 v[168:171], v188 offset:3072
	s_add_u32 s46, s44, 0x100
	s_addc_u32 s47, s45, 0
	s_cmp_eq_u32 s63, 28
	s_cselect_b32 s51, s21, s47
	s_cselect_b32 s50, s41, s46
	s_cselect_b32 s49, s19, s62
	s_cselect_b32 s48, s60, s61
	s_add_i32 m0, s4, 0xc000
	ds_read_b128 v[172:175], v189
	ds_read_b128 v[176:179], v189 offset:1024
	ds_read_b128 v[190:193], v189 offset:2048
	ds_read_b128 v[194:197], v189 offset:3072
	ds_read_b128 v[198:201], v189 offset:4096
	ds_read_b128 v[202:205], v189 offset:5120
	ds_read_b128 v[206:209], v189 offset:6144
	ds_read_b128 v[210:213], v189 offset:7168
	global_load_lds_dwordx4 v132, s[44:45]
	s_add_i32 m0, s4, 0xe000
	s_nop 0
	global_load_lds_dwordx4 v134, s[44:45]
	s_waitcnt vmcnt(8)
	s_waitcnt lgkmcnt(0)
	s_barrier
	s_setprio 3
	s_waitcnt lgkmcnt(0)
	v_mfma_f32_16x16x32_bf16 v[124:127], v[140:143], v[172:175], v[124:127]
	v_mfma_f32_16x16x32_bf16 v[120:123], v[148:151], v[172:175], v[120:123]
	v_mfma_f32_16x16x32_bf16 v[108:111], v[140:143], v[190:193], v[108:111]
	v_mfma_f32_16x16x32_bf16 v[104:107], v[148:151], v[190:193], v[104:107]
	v_mfma_f32_16x16x32_bf16 v[92:95], v[140:143], v[198:201], v[92:95]
	v_mfma_f32_16x16x32_bf16 v[88:91], v[148:151], v[198:201], v[88:91]
	v_mfma_f32_16x16x32_bf16 v[76:79], v[140:143], v[206:209], v[76:79]
	v_mfma_f32_16x16x32_bf16 v[72:75], v[148:151], v[206:209], v[72:75]
	v_mfma_f32_16x16x32_bf16 v[124:127], v[144:147], v[176:179], v[124:127]
	v_mfma_f32_16x16x32_bf16 v[120:123], v[152:155], v[176:179], v[120:123]
	v_mfma_f32_16x16x32_bf16 v[108:111], v[144:147], v[194:197], v[108:111]
	v_mfma_f32_16x16x32_bf16 v[104:107], v[152:155], v[194:197], v[104:107]
	v_mfma_f32_16x16x32_bf16 v[92:95], v[144:147], v[202:205], v[92:95]
	v_mfma_f32_16x16x32_bf16 v[88:91], v[152:155], v[202:205], v[88:91]
	v_mfma_f32_16x16x32_bf16 v[76:79], v[144:147], v[210:213], v[76:79]
	v_mfma_f32_16x16x32_bf16 v[72:75], v[152:155], v[210:213], v[72:75]
	s_setprio 0
	s_setprio 3
	v_mfma_f32_16x16x32_bf16 v[116:119], v[156:159], v[172:175], v[116:119]
	v_mfma_f32_16x16x32_bf16 v[112:115], v[164:167], v[172:175], v[112:115]
	v_mfma_f32_16x16x32_bf16 v[100:103], v[156:159], v[190:193], v[100:103]
	v_mfma_f32_16x16x32_bf16 v[96:99], v[164:167], v[190:193], v[96:99]
	v_mfma_f32_16x16x32_bf16 v[84:87], v[156:159], v[198:201], v[84:87]
	v_mfma_f32_16x16x32_bf16 v[80:83], v[164:167], v[198:201], v[80:83]
	v_mfma_f32_16x16x32_bf16 v[68:71], v[156:159], v[206:209], v[68:71]
	v_mfma_f32_16x16x32_bf16 v[64:67], v[164:167], v[206:209], v[64:67]
	v_mfma_f32_16x16x32_bf16 v[116:119], v[160:163], v[176:179], v[116:119]
	v_mfma_f32_16x16x32_bf16 v[112:115], v[168:171], v[176:179], v[112:115]
	v_mfma_f32_16x16x32_bf16 v[100:103], v[160:163], v[194:197], v[100:103]
	v_mfma_f32_16x16x32_bf16 v[96:99], v[168:171], v[194:197], v[96:99]
	v_mfma_f32_16x16x32_bf16 v[84:87], v[160:163], v[202:205], v[84:87]
	v_mfma_f32_16x16x32_bf16 v[80:83], v[168:171], v[202:205], v[80:83]
	v_mfma_f32_16x16x32_bf16 v[68:71], v[160:163], v[210:213], v[68:71]
	v_mfma_f32_16x16x32_bf16 v[64:67], v[168:171], v[210:213], v[64:67]
	s_setprio 0
	s_barrier
	s_add_u32 s98, s48, s16
	s_addc_u32 s99, s49, s17
	s_add_u32 s100, s50, s16
	s_addc_u32 s101, s51, s17
	s_add_i32 s44, s58, s89
	s_mov_b32 m0, s44
	ds_read_b128 v[172:175], v189 offset:16384
	ds_read_b128 v[176:179], v189 offset:17408
	ds_read_b128 v[190:193], v189 offset:18432
	ds_read_b128 v[194:197], v189 offset:19456
	ds_read_b128 v[198:201], v189 offset:20480
	ds_read_b128 v[202:205], v189 offset:21504
	ds_read_b128 v[206:209], v189 offset:22528
	ds_read_b128 v[210:213], v189 offset:23552
	global_load_lds_dwordx4 v128, s[48:49]
	s_add_i32 m0, s44, 0x2000
	s_add_u32 s44, s48, 0x80000
	s_addc_u32 s45, s49, 0
	s_add_i32 s68, s59, s89
	global_load_lds_dwordx4 v130, s[48:49]
	s_mov_b32 m0, s68
	s_nop 0
	global_load_lds_dwordx4 v128, s[44:45]
	s_add_i32 m0, s68, 0x2000
	s_nop 0
	global_load_lds_dwordx4 v130, s[44:45]
	s_mov_b32 m0, s4
	s_nop 0
	global_load_lds_dwordx4 v128, s[50:51]
	s_mov_b32 m0, s5
	s_nop 0
	global_load_lds_dwordx4 v130, s[50:51]
	s_waitcnt vmcnt(8)
	s_waitcnt lgkmcnt(0)
	s_barrier
	s_setprio 3
	s_waitcnt lgkmcnt(0)
	v_mfma_f32_16x16x32_bf16 v[60:63], v[140:143], v[172:175], v[60:63]
	v_mfma_f32_16x16x32_bf16 v[56:59], v[148:151], v[172:175], v[56:59]
	v_mfma_f32_16x16x32_bf16 v[44:47], v[140:143], v[190:193], v[44:47]
	v_mfma_f32_16x16x32_bf16 v[40:43], v[148:151], v[190:193], v[40:43]
	v_mfma_f32_16x16x32_bf16 v[28:31], v[140:143], v[198:201], v[28:31]
	v_mfma_f32_16x16x32_bf16 v[24:27], v[148:151], v[198:201], v[24:27]
	v_mfma_f32_16x16x32_bf16 v[12:15], v[140:143], v[206:209], v[12:15]
	v_mfma_f32_16x16x32_bf16 v[8:11], v[148:151], v[206:209], v[8:11]
	v_mfma_f32_16x16x32_bf16 v[60:63], v[144:147], v[176:179], v[60:63]
	v_mfma_f32_16x16x32_bf16 v[56:59], v[152:155], v[176:179], v[56:59]
	v_mfma_f32_16x16x32_bf16 v[44:47], v[144:147], v[194:197], v[44:47]
	v_mfma_f32_16x16x32_bf16 v[40:43], v[152:155], v[194:197], v[40:43]
	v_mfma_f32_16x16x32_bf16 v[28:31], v[144:147], v[202:205], v[28:31]
	v_mfma_f32_16x16x32_bf16 v[24:27], v[152:155], v[202:205], v[24:27]
	v_mfma_f32_16x16x32_bf16 v[12:15], v[144:147], v[210:213], v[12:15]
	v_mfma_f32_16x16x32_bf16 v[8:11], v[152:155], v[210:213], v[8:11]
	s_setprio 0
	s_setprio 3
	v_mfma_f32_16x16x32_bf16 v[52:55], v[156:159], v[172:175], v[52:55]
	v_mfma_f32_16x16x32_bf16 v[48:51], v[164:167], v[172:175], v[48:51]
	v_mfma_f32_16x16x32_bf16 v[36:39], v[156:159], v[190:193], v[36:39]
	v_mfma_f32_16x16x32_bf16 v[32:35], v[164:167], v[190:193], v[32:35]
	v_mfma_f32_16x16x32_bf16 v[20:23], v[156:159], v[198:201], v[20:23]
	v_mfma_f32_16x16x32_bf16 v[16:19], v[164:167], v[198:201], v[16:19]
	v_mfma_f32_16x16x32_bf16 v[4:7], v[156:159], v[206:209], v[4:7]
	v_mfma_f32_16x16x32_bf16 v[0:3], v[164:167], v[206:209], v[0:3]
	v_mfma_f32_16x16x32_bf16 v[52:55], v[160:163], v[176:179], v[52:55]
	v_mfma_f32_16x16x32_bf16 v[48:51], v[168:171], v[176:179], v[48:51]
	v_mfma_f32_16x16x32_bf16 v[36:39], v[160:163], v[194:197], v[36:39]
	v_mfma_f32_16x16x32_bf16 v[32:35], v[168:171], v[194:197], v[32:35]
	v_mfma_f32_16x16x32_bf16 v[20:23], v[160:163], v[202:205], v[20:23]
	v_mfma_f32_16x16x32_bf16 v[16:19], v[168:171], v[202:205], v[16:19]
	v_mfma_f32_16x16x32_bf16 v[4:7], v[160:163], v[210:213], v[4:7]
	v_mfma_f32_16x16x32_bf16 v[0:3], v[168:171], v[210:213], v[0:3]
	s_setprio 0
	s_barrier
	s_add_i32 s68, 0, 0x18000
	s_add_i32 s69, 0, 0x1c000
	v_add_u32_e32 v152, s68, v183
	v_add_u32_e32 v168, s69, v183
	ds_read_b128 v[140:143], v152
	ds_read_b128 v[144:147], v152 offset:1024
	ds_read_b128 v[148:151], v152 offset:2048
	ds_read_b128 v[152:155], v152 offset:3072
	ds_read_b128 v[156:159], v168
	ds_read_b128 v[160:163], v168 offset:1024
	ds_read_b128 v[164:167], v168 offset:2048
	ds_read_b128 v[168:171], v168 offset:3072
	s_add_u32 s44, s50, 0x80000
	s_addc_u32 s45, s51, 0
	s_mov_b32 m0, s28
	ds_read_b128 v[172:175], v189 offset:32768
	ds_read_b128 v[176:179], v189 offset:33792
	ds_read_b128 v[190:193], v189 offset:34816
	ds_read_b128 v[194:197], v189 offset:35840
	ds_read_b128 v[198:201], v189 offset:36864
	ds_read_b128 v[202:205], v189 offset:37888
	ds_read_b128 v[206:209], v189 offset:38912
	ds_read_b128 v[210:213], v189 offset:39936
	global_load_lds_dwordx4 v128, s[44:45]
	s_mov_b32 m0, s29
	s_nop 0
	global_load_lds_dwordx4 v130, s[44:45]
	s_waitcnt vmcnt(8)
	s_waitcnt lgkmcnt(0)
	s_barrier
	s_setprio 3
	s_waitcnt lgkmcnt(0)
	v_mfma_f32_16x16x32_bf16 v[124:127], v[140:143], v[172:175], v[124:127]
	v_mfma_f32_16x16x32_bf16 v[120:123], v[148:151], v[172:175], v[120:123]
	v_mfma_f32_16x16x32_bf16 v[108:111], v[140:143], v[190:193], v[108:111]
	v_mfma_f32_16x16x32_bf16 v[104:107], v[148:151], v[190:193], v[104:107]
	v_mfma_f32_16x16x32_bf16 v[92:95], v[140:143], v[198:201], v[92:95]
	v_mfma_f32_16x16x32_bf16 v[88:91], v[148:151], v[198:201], v[88:91]
	v_mfma_f32_16x16x32_bf16 v[76:79], v[140:143], v[206:209], v[76:79]
	v_mfma_f32_16x16x32_bf16 v[72:75], v[148:151], v[206:209], v[72:75]
	v_mfma_f32_16x16x32_bf16 v[124:127], v[144:147], v[176:179], v[124:127]
	v_mfma_f32_16x16x32_bf16 v[120:123], v[152:155], v[176:179], v[120:123]
	v_mfma_f32_16x16x32_bf16 v[108:111], v[144:147], v[194:197], v[108:111]
	v_mfma_f32_16x16x32_bf16 v[104:107], v[152:155], v[194:197], v[104:107]
	v_mfma_f32_16x16x32_bf16 v[92:95], v[144:147], v[202:205], v[92:95]
	v_mfma_f32_16x16x32_bf16 v[88:91], v[152:155], v[202:205], v[88:91]
	v_mfma_f32_16x16x32_bf16 v[76:79], v[144:147], v[210:213], v[76:79]
	v_mfma_f32_16x16x32_bf16 v[72:75], v[152:155], v[210:213], v[72:75]
	s_setprio 0
	s_setprio 3
	v_mfma_f32_16x16x32_bf16 v[116:119], v[156:159], v[172:175], v[116:119]
	v_mfma_f32_16x16x32_bf16 v[112:115], v[164:167], v[172:175], v[112:115]
	v_mfma_f32_16x16x32_bf16 v[100:103], v[156:159], v[190:193], v[100:103]
	v_mfma_f32_16x16x32_bf16 v[96:99], v[164:167], v[190:193], v[96:99]
	v_mfma_f32_16x16x32_bf16 v[84:87], v[156:159], v[198:201], v[84:87]
	v_mfma_f32_16x16x32_bf16 v[80:83], v[164:167], v[198:201], v[80:83]
	v_mfma_f32_16x16x32_bf16 v[68:71], v[156:159], v[206:209], v[68:71]
	v_mfma_f32_16x16x32_bf16 v[64:67], v[164:167], v[206:209], v[64:67]
	v_mfma_f32_16x16x32_bf16 v[116:119], v[160:163], v[176:179], v[116:119]
	v_mfma_f32_16x16x32_bf16 v[112:115], v[168:171], v[176:179], v[112:115]
	v_mfma_f32_16x16x32_bf16 v[100:103], v[160:163], v[194:197], v[100:103]
	v_mfma_f32_16x16x32_bf16 v[96:99], v[168:171], v[194:197], v[96:99]
	v_mfma_f32_16x16x32_bf16 v[84:87], v[160:163], v[202:205], v[84:87]
	v_mfma_f32_16x16x32_bf16 v[80:83], v[168:171], v[202:205], v[80:83]
	v_mfma_f32_16x16x32_bf16 v[68:71], v[160:163], v[210:213], v[68:71]
	v_mfma_f32_16x16x32_bf16 v[64:67], v[168:171], v[210:213], v[64:67]
	s_setprio 0
	s_barrier
	s_add_i32 s44, s68, s89
	s_mov_b32 m0, s44
	ds_read_b128 v[172:175], v189 offset:49152
	ds_read_b128 v[176:179], v189 offset:50176
	ds_read_b128 v[190:193], v189 offset:51200
	ds_read_b128 v[194:197], v189 offset:52224
	ds_read_b128 v[198:201], v189 offset:53248
	ds_read_b128 v[202:205], v189 offset:54272
	ds_read_b128 v[206:209], v189 offset:55296
	ds_read_b128 v[210:213], v189 offset:56320
	global_load_lds_dwordx4 v128, s[98:99]
	s_add_i32 m0, s44, 0x2000
	s_add_u32 s44, s48, 0x80080
	s_addc_u32 s45, s49, 0
	s_add_i32 s48, s69, s89
	global_load_lds_dwordx4 v130, s[98:99]
	s_mov_b32 m0, s48
	s_nop 0
	global_load_lds_dwordx4 v128, s[44:45]
	s_add_i32 m0, s48, 0x2000
	s_nop 0
	global_load_lds_dwordx4 v130, s[44:45]
	s_mov_b32 m0, s56
	s_nop 0
	global_load_lds_dwordx4 v128, s[100:101]
	s_mov_b32 m0, s57
	s_nop 0
	global_load_lds_dwordx4 v130, s[100:101]
	s_waitcnt vmcnt(8)
	s_waitcnt lgkmcnt(0)
	s_barrier
	s_setprio 3
	s_waitcnt lgkmcnt(0)
	v_mfma_f32_16x16x32_bf16 v[60:63], v[140:143], v[172:175], v[60:63]
	v_mfma_f32_16x16x32_bf16 v[56:59], v[148:151], v[172:175], v[56:59]
	v_mfma_f32_16x16x32_bf16 v[44:47], v[140:143], v[190:193], v[44:47]
	v_mfma_f32_16x16x32_bf16 v[40:43], v[148:151], v[190:193], v[40:43]
	v_mfma_f32_16x16x32_bf16 v[28:31], v[140:143], v[198:201], v[28:31]
	v_mfma_f32_16x16x32_bf16 v[24:27], v[148:151], v[198:201], v[24:27]
	v_mfma_f32_16x16x32_bf16 v[12:15], v[140:143], v[206:209], v[12:15]
	v_mfma_f32_16x16x32_bf16 v[8:11], v[148:151], v[206:209], v[8:11]
	v_mfma_f32_16x16x32_bf16 v[60:63], v[144:147], v[176:179], v[60:63]
	v_mfma_f32_16x16x32_bf16 v[56:59], v[152:155], v[176:179], v[56:59]
	v_mfma_f32_16x16x32_bf16 v[44:47], v[144:147], v[194:197], v[44:47]
	v_mfma_f32_16x16x32_bf16 v[40:43], v[152:155], v[194:197], v[40:43]
	v_mfma_f32_16x16x32_bf16 v[28:31], v[144:147], v[202:205], v[28:31]
	v_mfma_f32_16x16x32_bf16 v[24:27], v[152:155], v[202:205], v[24:27]
	v_mfma_f32_16x16x32_bf16 v[12:15], v[144:147], v[210:213], v[12:15]
	v_mfma_f32_16x16x32_bf16 v[8:11], v[152:155], v[210:213], v[8:11]
	s_setprio 0
	s_setprio 3
	v_mfma_f32_16x16x32_bf16 v[52:55], v[156:159], v[172:175], v[52:55]
	v_mfma_f32_16x16x32_bf16 v[48:51], v[164:167], v[172:175], v[48:51]
	v_mfma_f32_16x16x32_bf16 v[36:39], v[156:159], v[190:193], v[36:39]
	v_mfma_f32_16x16x32_bf16 v[32:35], v[164:167], v[190:193], v[32:35]
	v_mfma_f32_16x16x32_bf16 v[20:23], v[156:159], v[198:201], v[20:23]
	v_mfma_f32_16x16x32_bf16 v[16:19], v[164:167], v[198:201], v[16:19]
	v_mfma_f32_16x16x32_bf16 v[4:7], v[156:159], v[206:209], v[4:7]
	v_mfma_f32_16x16x32_bf16 v[0:3], v[164:167], v[206:209], v[0:3]
	v_mfma_f32_16x16x32_bf16 v[52:55], v[160:163], v[176:179], v[52:55]
	v_mfma_f32_16x16x32_bf16 v[48:51], v[168:171], v[176:179], v[48:51]
	v_mfma_f32_16x16x32_bf16 v[36:39], v[160:163], v[194:197], v[36:39]
	v_mfma_f32_16x16x32_bf16 v[32:35], v[168:171], v[194:197], v[32:35]
	v_mfma_f32_16x16x32_bf16 v[20:23], v[160:163], v[202:205], v[20:23]
	v_mfma_f32_16x16x32_bf16 v[16:19], v[168:171], v[202:205], v[16:19]
	v_mfma_f32_16x16x32_bf16 v[4:7], v[160:163], v[210:213], v[4:7]
	v_mfma_f32_16x16x32_bf16 v[0:3], v[168:171], v[210:213], v[0:3]
	s_setprio 0
	s_barrier
	s_add_i32 s63, s63, 2
	s_add_u32 s61, s61, 0x100
	s_addc_u32 s62, s62, 0
	s_cmp_gt_u32 s63, 29
	s_mov_b64 s[44:45], s[46:47]
	s_cbranch_scc0 .LBB0_750
	s_and_b64 vcc, exec, s[64:65]
	s_cbranch_vccz .LBB0_753
	s_barrier

.LBB0_836:
	ds_read_b128 v[144:147], v157
	ds_read_b128 v[162:165], v157 offset:1024
	ds_read_b128 v[166:169], v157 offset:2048
	ds_read_b128 v[170:173], v157 offset:3072
	ds_read_b128 v[174:177], v159
	ds_read_b128 v[178:181], v159 offset:1024
	ds_read_b128 v[182:185], v159 offset:2048
	ds_read_b128 v[186:189], v159 offset:3072
	s_add_u32 s40, s38, 0xfff80080
	s_addc_u32 s41, s39, -1
	s_cmp_eq_u32 s59, 28
	s_cselect_b32 s43, s17, s41
	s_cselect_b32 s42, s51, s40
	s_cselect_b32 s41, s15, s58
	s_cselect_b32 s40, s56, s57
	s_add_i32 m0, s5, 0xc000
	ds_read_b128 v[190:193], v160
	ds_read_b128 v[194:197], v160 offset:1024
	ds_read_b128 v[198:201], v160 offset:2048
	ds_read_b128 v[202:205], v160 offset:3072
	ds_read_b128 v[206:209], v160 offset:4096
	ds_read_b128 v[210:213], v160 offset:5120
	ds_read_b128 v[214:217], v160 offset:6144
	ds_read_b128 v[218:221], v160 offset:7168
	global_load_lds_dwordx4 v136, s[38:39]
	s_add_i32 m0, s5, 0xe000
	s_nop 0
	global_load_lds_dwordx4 v138, s[38:39]
	s_waitcnt vmcnt(8)
	s_waitcnt lgkmcnt(0)
	s_barrier
	s_setprio 3
	s_waitcnt lgkmcnt(0)
	v_mfma_f32_16x16x32_bf16 v[124:127], v[144:147], v[190:193], v[124:127]
	v_mfma_f32_16x16x32_bf16 v[120:123], v[166:169], v[190:193], v[120:123]
	v_mfma_f32_16x16x32_bf16 v[116:119], v[144:147], v[198:201], v[116:119]
	v_mfma_f32_16x16x32_bf16 v[112:115], v[166:169], v[198:201], v[112:115]
	v_mfma_f32_16x16x32_bf16 v[92:95], v[144:147], v[206:209], v[92:95]
	v_mfma_f32_16x16x32_bf16 v[88:91], v[166:169], v[206:209], v[88:91]
	v_mfma_f32_16x16x32_bf16 v[76:79], v[144:147], v[214:217], v[76:79]
	v_mfma_f32_16x16x32_bf16 v[72:75], v[166:169], v[214:217], v[72:75]
	v_mfma_f32_16x16x32_bf16 v[124:127], v[162:165], v[194:197], v[124:127]
	v_mfma_f32_16x16x32_bf16 v[120:123], v[170:173], v[194:197], v[120:123]
	v_mfma_f32_16x16x32_bf16 v[116:119], v[162:165], v[202:205], v[116:119]
	v_mfma_f32_16x16x32_bf16 v[112:115], v[170:173], v[202:205], v[112:115]
	v_mfma_f32_16x16x32_bf16 v[92:95], v[162:165], v[210:213], v[92:95]
	v_mfma_f32_16x16x32_bf16 v[88:91], v[170:173], v[210:213], v[88:91]
	v_mfma_f32_16x16x32_bf16 v[76:79], v[162:165], v[218:221], v[76:79]
	v_mfma_f32_16x16x32_bf16 v[72:75], v[170:173], v[218:221], v[72:75]
	s_setprio 0
	s_setprio 3
	v_mfma_f32_16x16x32_bf16 v[108:111], v[174:177], v[190:193], v[108:111]
	v_mfma_f32_16x16x32_bf16 v[104:107], v[182:185], v[190:193], v[104:107]
	v_mfma_f32_16x16x32_bf16 v[100:103], v[174:177], v[198:201], v[100:103]
	v_mfma_f32_16x16x32_bf16 v[96:99], v[182:185], v[198:201], v[96:99]
	v_mfma_f32_16x16x32_bf16 v[84:87], v[174:177], v[206:209], v[84:87]
	v_mfma_f32_16x16x32_bf16 v[80:83], v[182:185], v[206:209], v[80:83]
	v_mfma_f32_16x16x32_bf16 v[68:71], v[174:177], v[214:217], v[68:71]
	v_mfma_f32_16x16x32_bf16 v[64:67], v[182:185], v[214:217], v[64:67]
	v_mfma_f32_16x16x32_bf16 v[108:111], v[178:181], v[194:197], v[108:111]
	v_mfma_f32_16x16x32_bf16 v[104:107], v[186:189], v[194:197], v[104:107]
	v_mfma_f32_16x16x32_bf16 v[100:103], v[178:181], v[202:205], v[100:103]
	v_mfma_f32_16x16x32_bf16 v[96:99], v[186:189], v[202:205], v[96:99]
	v_mfma_f32_16x16x32_bf16 v[84:87], v[178:181], v[210:213], v[84:87]
	v_mfma_f32_16x16x32_bf16 v[80:83], v[186:189], v[210:213], v[80:83]
	v_mfma_f32_16x16x32_bf16 v[68:71], v[178:181], v[218:221], v[68:71]
	v_mfma_f32_16x16x32_bf16 v[64:67], v[186:189], v[218:221], v[64:67]
	s_setprio 0
	s_barrier
	s_add_u32 s98, s40, s10
	s_addc_u32 s99, s41, s11
	s_add_u32 s100, s42, s10
	s_addc_u32 s101, s43, s11
	s_add_i32 s60, s47, s89
	s_mov_b32 m0, s60
	ds_read_b128 v[190:193], v160 offset:16384
	ds_read_b128 v[194:197], v160 offset:17408
	ds_read_b128 v[198:201], v160 offset:18432
	ds_read_b128 v[202:205], v160 offset:19456
	ds_read_b128 v[206:209], v160 offset:20480
	ds_read_b128 v[210:213], v160 offset:21504
	ds_read_b128 v[214:217], v160 offset:22528
	ds_read_b128 v[218:221], v160 offset:23552
	global_load_lds_dwordx4 v128, s[40:41]
	s_add_i32 m0, s60, 0x2000
	s_add_u32 s60, s40, 0x80000
	s_addc_u32 s61, s41, 0
	s_add_i32 s62, s48, s89
	global_load_lds_dwordx4 v130, s[40:41]
	s_mov_b32 m0, s62
	s_nop 0
	global_load_lds_dwordx4 v128, s[60:61]
	s_add_i32 m0, s62, 0x2000
	s_nop 0
	global_load_lds_dwordx4 v130, s[60:61]
	s_mov_b32 m0, s5
	s_nop 0
	global_load_lds_dwordx4 v134, s[42:43]
	s_mov_b32 m0, s28
	s_nop 0
	global_load_lds_dwordx4 v132, s[42:43]
	s_waitcnt vmcnt(8)
	s_waitcnt lgkmcnt(0)
	s_barrier
	s_setprio 3
	s_waitcnt lgkmcnt(0)
	v_mfma_f32_16x16x32_bf16 v[60:63], v[144:147], v[190:193], v[60:63]
	v_mfma_f32_16x16x32_bf16 v[56:59], v[166:169], v[190:193], v[56:59]
	v_mfma_f32_16x16x32_bf16 v[44:47], v[144:147], v[198:201], v[44:47]
	v_mfma_f32_16x16x32_bf16 v[40:43], v[166:169], v[198:201], v[40:43]
	v_mfma_f32_16x16x32_bf16 v[28:31], v[144:147], v[206:209], v[28:31]
	v_mfma_f32_16x16x32_bf16 v[24:27], v[166:169], v[206:209], v[24:27]
	v_mfma_f32_16x16x32_bf16 v[12:15], v[144:147], v[214:217], v[12:15]
	v_mfma_f32_16x16x32_bf16 v[8:11], v[166:169], v[214:217], v[8:11]
	v_mfma_f32_16x16x32_bf16 v[60:63], v[162:165], v[194:197], v[60:63]
	v_mfma_f32_16x16x32_bf16 v[56:59], v[170:173], v[194:197], v[56:59]
	v_mfma_f32_16x16x32_bf16 v[44:47], v[162:165], v[202:205], v[44:47]
	v_mfma_f32_16x16x32_bf16 v[40:43], v[170:173], v[202:205], v[40:43]
	v_mfma_f32_16x16x32_bf16 v[28:31], v[162:165], v[210:213], v[28:31]
	v_mfma_f32_16x16x32_bf16 v[24:27], v[170:173], v[210:213], v[24:27]
	v_mfma_f32_16x16x32_bf16 v[12:15], v[162:165], v[218:221], v[12:15]
	v_mfma_f32_16x16x32_bf16 v[8:11], v[170:173], v[218:221], v[8:11]
	s_setprio 0
	s_setprio 3
	v_mfma_f32_16x16x32_bf16 v[52:55], v[174:177], v[190:193], v[52:55]
	v_mfma_f32_16x16x32_bf16 v[48:51], v[182:185], v[190:193], v[48:51]
	v_mfma_f32_16x16x32_bf16 v[36:39], v[174:177], v[198:201], v[36:39]
	v_mfma_f32_16x16x32_bf16 v[32:35], v[182:185], v[198:201], v[32:35]
	v_mfma_f32_16x16x32_bf16 v[20:23], v[174:177], v[206:209], v[20:23]
	v_mfma_f32_16x16x32_bf16 v[16:19], v[182:185], v[206:209], v[16:19]
	v_mfma_f32_16x16x32_bf16 v[4:7], v[174:177], v[214:217], v[4:7]
	v_mfma_f32_16x16x32_bf16 v[0:3], v[182:185], v[214:217], v[0:3]
	v_mfma_f32_16x16x32_bf16 v[52:55], v[178:181], v[194:197], v[52:55]
	v_mfma_f32_16x16x32_bf16 v[48:51], v[186:189], v[194:197], v[48:51]
	v_mfma_f32_16x16x32_bf16 v[36:39], v[178:181], v[202:205], v[36:39]
	v_mfma_f32_16x16x32_bf16 v[32:35], v[186:189], v[202:205], v[32:35]
	v_mfma_f32_16x16x32_bf16 v[20:23], v[178:181], v[210:213], v[20:23]
	v_mfma_f32_16x16x32_bf16 v[16:19], v[186:189], v[210:213], v[16:19]
	v_mfma_f32_16x16x32_bf16 v[4:7], v[178:181], v[218:221], v[4:7]
	v_mfma_f32_16x16x32_bf16 v[0:3], v[186:189], v[218:221], v[0:3]
	s_setprio 0
	s_barrier
	s_add_i32 s60, 0, 0x18000
	v_add_u32_e32 v150, s60, v153
	s_add_i32 s61, 0, 0x1c000
	ds_read_b128 v[144:147], v150
	ds_read_b128 v[162:165], v150 offset:1024
	ds_read_b128 v[166:169], v150 offset:2048
	ds_read_b128 v[170:173], v150 offset:3072
	v_add_u32_e32 v150, s61, v153
	ds_read_b128 v[174:177], v150
	ds_read_b128 v[178:181], v150 offset:1024
	ds_read_b128 v[182:185], v150 offset:2048
	ds_read_b128 v[186:189], v150 offset:3072
	s_add_u32 s42, s42, 0x80000
	s_addc_u32 s43, s43, 0
	s_mov_b32 m0, s29
	ds_read_b128 v[190:193], v160 offset:32768
	ds_read_b128 v[194:197], v160 offset:33792
	ds_read_b128 v[198:201], v160 offset:34816
	ds_read_b128 v[202:205], v160 offset:35840
	ds_read_b128 v[206:209], v160 offset:36864
	ds_read_b128 v[210:213], v160 offset:37888
	ds_read_b128 v[214:217], v160 offset:38912
	ds_read_b128 v[218:221], v160 offset:39936
	global_load_lds_dwordx4 v134, s[42:43]
	s_mov_b32 m0, s37
	s_nop 0
	global_load_lds_dwordx4 v132, s[42:43]
	s_waitcnt vmcnt(8)
	s_waitcnt lgkmcnt(0)
	s_barrier
	s_setprio 3
	s_waitcnt lgkmcnt(0)
	v_mfma_f32_16x16x32_bf16 v[124:127], v[144:147], v[190:193], v[124:127]
	v_mfma_f32_16x16x32_bf16 v[120:123], v[166:169], v[190:193], v[120:123]
	v_mfma_f32_16x16x32_bf16 v[116:119], v[144:147], v[198:201], v[116:119]
	v_mfma_f32_16x16x32_bf16 v[112:115], v[166:169], v[198:201], v[112:115]
	v_mfma_f32_16x16x32_bf16 v[92:95], v[144:147], v[206:209], v[92:95]
	v_mfma_f32_16x16x32_bf16 v[88:91], v[166:169], v[206:209], v[88:91]
	v_mfma_f32_16x16x32_bf16 v[76:79], v[144:147], v[214:217], v[76:79]
	v_mfma_f32_16x16x32_bf16 v[72:75], v[166:169], v[214:217], v[72:75]
	v_mfma_f32_16x16x32_bf16 v[124:127], v[162:165], v[194:197], v[124:127]
	v_mfma_f32_16x16x32_bf16 v[120:123], v[170:173], v[194:197], v[120:123]
	v_mfma_f32_16x16x32_bf16 v[116:119], v[162:165], v[202:205], v[116:119]
	v_mfma_f32_16x16x32_bf16 v[112:115], v[170:173], v[202:205], v[112:115]
	v_mfma_f32_16x16x32_bf16 v[92:95], v[162:165], v[210:213], v[92:95]
	v_mfma_f32_16x16x32_bf16 v[88:91], v[170:173], v[210:213], v[88:91]
	v_mfma_f32_16x16x32_bf16 v[76:79], v[162:165], v[218:221], v[76:79]
	v_mfma_f32_16x16x32_bf16 v[72:75], v[170:173], v[218:221], v[72:75]
	s_setprio 0
	s_setprio 3
	v_mfma_f32_16x16x32_bf16 v[108:111], v[174:177], v[190:193], v[108:111]
	v_mfma_f32_16x16x32_bf16 v[104:107], v[182:185], v[190:193], v[104:107]
	v_mfma_f32_16x16x32_bf16 v[100:103], v[174:177], v[198:201], v[100:103]
	v_mfma_f32_16x16x32_bf16 v[96:99], v[182:185], v[198:201], v[96:99]
	v_mfma_f32_16x16x32_bf16 v[84:87], v[174:177], v[206:209], v[84:87]
	v_mfma_f32_16x16x32_bf16 v[80:83], v[182:185], v[206:209], v[80:83]
	v_mfma_f32_16x16x32_bf16 v[68:71], v[174:177], v[214:217], v[68:71]
	v_mfma_f32_16x16x32_bf16 v[64:67], v[182:185], v[214:217], v[64:67]
	v_mfma_f32_16x16x32_bf16 v[108:111], v[178:181], v[194:197], v[108:111]
	v_mfma_f32_16x16x32_bf16 v[104:107], v[186:189], v[194:197], v[104:107]
	v_mfma_f32_16x16x32_bf16 v[100:103], v[178:181], v[202:205], v[100:103]
	v_mfma_f32_16x16x32_bf16 v[96:99], v[186:189], v[202:205], v[96:99]
	v_mfma_f32_16x16x32_bf16 v[84:87], v[178:181], v[210:213], v[84:87]
	v_mfma_f32_16x16x32_bf16 v[80:83], v[186:189], v[210:213], v[80:83]
	v_mfma_f32_16x16x32_bf16 v[68:71], v[178:181], v[218:221], v[68:71]
	v_mfma_f32_16x16x32_bf16 v[64:67], v[186:189], v[218:221], v[64:67]
	s_setprio 0
	s_barrier
	s_add_i32 s42, s60, s89
	s_mov_b32 m0, s42
	ds_read_b128 v[190:193], v160 offset:49152
	ds_read_b128 v[194:197], v160 offset:50176
	ds_read_b128 v[198:201], v160 offset:51200
	ds_read_b128 v[202:205], v160 offset:52224
	ds_read_b128 v[206:209], v160 offset:53248
	ds_read_b128 v[210:213], v160 offset:54272
	ds_read_b128 v[214:217], v160 offset:55296
	ds_read_b128 v[218:221], v160 offset:56320
	global_load_lds_dwordx4 v128, s[98:99]
	s_add_i32 m0, s42, 0x2000
	s_add_u32 s40, s40, 0x80080
	s_addc_u32 s41, s41, 0
	s_add_i32 s42, s61, s89
	global_load_lds_dwordx4 v130, s[98:99]
	s_mov_b32 m0, s42
	s_nop 0
	global_load_lds_dwordx4 v128, s[40:41]
	s_add_i32 m0, s42, 0x2000
	s_nop 0
	global_load_lds_dwordx4 v130, s[40:41]
	s_mov_b32 m0, s45
	s_nop 0
	global_load_lds_dwordx4 v134, s[100:101]
	s_mov_b32 m0, s46
	s_nop 0
	global_load_lds_dwordx4 v132, s[100:101]
	s_waitcnt vmcnt(8)
	s_waitcnt lgkmcnt(0)
	s_barrier
	s_setprio 3
	s_waitcnt lgkmcnt(0)
	v_mfma_f32_16x16x32_bf16 v[60:63], v[144:147], v[190:193], v[60:63]
	v_mfma_f32_16x16x32_bf16 v[56:59], v[166:169], v[190:193], v[56:59]
	v_mfma_f32_16x16x32_bf16 v[44:47], v[144:147], v[198:201], v[44:47]
	v_mfma_f32_16x16x32_bf16 v[40:43], v[166:169], v[198:201], v[40:43]
	v_mfma_f32_16x16x32_bf16 v[28:31], v[144:147], v[206:209], v[28:31]
	v_mfma_f32_16x16x32_bf16 v[24:27], v[166:169], v[206:209], v[24:27]
	v_mfma_f32_16x16x32_bf16 v[12:15], v[144:147], v[214:217], v[12:15]
	v_mfma_f32_16x16x32_bf16 v[8:11], v[166:169], v[214:217], v[8:11]
	v_mfma_f32_16x16x32_bf16 v[60:63], v[162:165], v[194:197], v[60:63]
	v_mfma_f32_16x16x32_bf16 v[56:59], v[170:173], v[194:197], v[56:59]
	v_mfma_f32_16x16x32_bf16 v[44:47], v[162:165], v[202:205], v[44:47]
	v_mfma_f32_16x16x32_bf16 v[40:43], v[170:173], v[202:205], v[40:43]
	v_mfma_f32_16x16x32_bf16 v[28:31], v[162:165], v[210:213], v[28:31]
	v_mfma_f32_16x16x32_bf16 v[24:27], v[170:173], v[210:213], v[24:27]
	v_mfma_f32_16x16x32_bf16 v[12:15], v[162:165], v[218:221], v[12:15]
	v_mfma_f32_16x16x32_bf16 v[8:11], v[170:173], v[218:221], v[8:11]
	s_setprio 0
	s_setprio 3
	v_mfma_f32_16x16x32_bf16 v[52:55], v[174:177], v[190:193], v[52:55]
	v_mfma_f32_16x16x32_bf16 v[48:51], v[182:185], v[190:193], v[48:51]
	v_mfma_f32_16x16x32_bf16 v[36:39], v[174:177], v[198:201], v[36:39]
	v_mfma_f32_16x16x32_bf16 v[32:35], v[182:185], v[198:201], v[32:35]
	v_mfma_f32_16x16x32_bf16 v[20:23], v[174:177], v[206:209], v[20:23]
	v_mfma_f32_16x16x32_bf16 v[16:19], v[182:185], v[206:209], v[16:19]
	v_mfma_f32_16x16x32_bf16 v[4:7], v[174:177], v[214:217], v[4:7]
	v_mfma_f32_16x16x32_bf16 v[0:3], v[182:185], v[214:217], v[0:3]
	v_mfma_f32_16x16x32_bf16 v[52:55], v[178:181], v[194:197], v[52:55]
	v_mfma_f32_16x16x32_bf16 v[48:51], v[186:189], v[194:197], v[48:51]
	v_mfma_f32_16x16x32_bf16 v[36:39], v[178:181], v[202:205], v[36:39]
	v_mfma_f32_16x16x32_bf16 v[32:35], v[186:189], v[202:205], v[32:35]
	v_mfma_f32_16x16x32_bf16 v[20:23], v[178:181], v[210:213], v[20:23]
	v_mfma_f32_16x16x32_bf16 v[16:19], v[186:189], v[210:213], v[16:19]
	v_mfma_f32_16x16x32_bf16 v[4:7], v[178:181], v[218:221], v[4:7]
	v_mfma_f32_16x16x32_bf16 v[0:3], v[186:189], v[218:221], v[0:3]
	s_setprio 0
	s_barrier
	s_add_i32 s59, s59, 2
	s_add_u32 s38, s38, 0x100
	s_addc_u32 s39, s39, 0
	s_add_u32 s57, s57, 0x100
	s_addc_u32 s58, s58, 0
	s_cmp_gt_u32 s59, 29
	s_cbranch_scc0 .LBB0_836
	s_and_b64 vcc, exec, s[64:65]
	s_cbranch_vccz .LBB0_839
	s_barrier

.LBB0_926:
	ds_read_b128 v[140:143], v147
	ds_read_b128 v[150:153], v147 offset:1024
	ds_read_b128 v[154:157], v147 offset:2048
	ds_read_b128 v[158:161], v147 offset:3072
	ds_read_b128 v[162:165], v148
	ds_read_b128 v[166:169], v148 offset:1024
	ds_read_b128 v[170:173], v148 offset:2048
	ds_read_b128 v[174:177], v148 offset:3072
	s_add_u32 s16, s14, 0x100
	s_addc_u32 s17, s15, 0
	s_cmpk_eq_i32 s43, 0x54
	s_cselect_b32 s21, s5, s17
	s_cselect_b32 s20, s4, s16
	s_cselect_b32 s19, s13, s42
	s_cselect_b32 s18, s12, s41
	s_add_i32 m0, s3, 0xc000
	ds_read_b128 v[178:181], v149
	ds_read_b128 v[182:185], v149 offset:1024
	ds_read_b128 v[186:189], v149 offset:2048
	ds_read_b128 v[190:193], v149 offset:3072
	ds_read_b128 v[194:197], v149 offset:4096
	ds_read_b128 v[198:201], v149 offset:5120
	ds_read_b128 v[202:205], v149 offset:6144
	ds_read_b128 v[206:209], v149 offset:7168
	global_load_lds_dwordx4 v132, s[14:15]
	s_add_i32 m0, s3, 0xe000
	s_nop 0
	global_load_lds_dwordx4 v134, s[14:15]
	s_waitcnt vmcnt(8)
	s_waitcnt lgkmcnt(0)
	s_barrier
	s_setprio 3
	s_waitcnt lgkmcnt(0)
	v_mfma_f32_16x16x32_bf16 v[124:127], v[140:143], v[178:181], v[124:127]
	v_mfma_f32_16x16x32_bf16 v[120:123], v[154:157], v[178:181], v[120:123]
	v_mfma_f32_16x16x32_bf16 v[112:115], v[140:143], v[186:189], v[112:115]
	v_mfma_f32_16x16x32_bf16 v[104:107], v[154:157], v[186:189], v[104:107]
	v_mfma_f32_16x16x32_bf16 v[96:99], v[140:143], v[194:197], v[96:99]
	v_mfma_f32_16x16x32_bf16 v[88:91], v[154:157], v[194:197], v[88:91]
	v_mfma_f32_16x16x32_bf16 v[80:83], v[140:143], v[202:205], v[80:83]
	v_mfma_f32_16x16x32_bf16 v[72:75], v[154:157], v[202:205], v[72:75]
	v_mfma_f32_16x16x32_bf16 v[124:127], v[150:153], v[182:185], v[124:127]
	v_mfma_f32_16x16x32_bf16 v[120:123], v[158:161], v[182:185], v[120:123]
	v_mfma_f32_16x16x32_bf16 v[112:115], v[150:153], v[190:193], v[112:115]
	v_mfma_f32_16x16x32_bf16 v[104:107], v[158:161], v[190:193], v[104:107]
	v_mfma_f32_16x16x32_bf16 v[96:99], v[150:153], v[198:201], v[96:99]
	v_mfma_f32_16x16x32_bf16 v[88:91], v[158:161], v[198:201], v[88:91]
	v_mfma_f32_16x16x32_bf16 v[80:83], v[150:153], v[206:209], v[80:83]
	v_mfma_f32_16x16x32_bf16 v[72:75], v[158:161], v[206:209], v[72:75]
	s_setprio 0
	s_setprio 3
	v_mfma_f32_16x16x32_bf16 v[116:119], v[162:165], v[178:181], v[116:119]
	v_mfma_f32_16x16x32_bf16 v[108:111], v[170:173], v[178:181], v[108:111]
	v_mfma_f32_16x16x32_bf16 v[100:103], v[162:165], v[186:189], v[100:103]
	v_mfma_f32_16x16x32_bf16 v[92:95], v[170:173], v[186:189], v[92:95]
	v_mfma_f32_16x16x32_bf16 v[84:87], v[162:165], v[194:197], v[84:87]
	v_mfma_f32_16x16x32_bf16 v[76:79], v[170:173], v[194:197], v[76:79]
	v_mfma_f32_16x16x32_bf16 v[68:71], v[162:165], v[202:205], v[68:71]
	v_mfma_f32_16x16x32_bf16 v[64:67], v[170:173], v[202:205], v[64:67]
	v_mfma_f32_16x16x32_bf16 v[116:119], v[166:169], v[182:185], v[116:119]
	v_mfma_f32_16x16x32_bf16 v[108:111], v[174:177], v[182:185], v[108:111]
	v_mfma_f32_16x16x32_bf16 v[100:103], v[166:169], v[190:193], v[100:103]
	v_mfma_f32_16x16x32_bf16 v[92:95], v[174:177], v[190:193], v[92:95]
	v_mfma_f32_16x16x32_bf16 v[84:87], v[166:169], v[198:201], v[84:87]
	v_mfma_f32_16x16x32_bf16 v[76:79], v[174:177], v[198:201], v[76:79]
	v_mfma_f32_16x16x32_bf16 v[68:71], v[166:169], v[206:209], v[68:71]
	v_mfma_f32_16x16x32_bf16 v[64:67], v[174:177], v[206:209], v[64:67]
	s_setprio 0
	s_barrier
	s_add_u32 s98, s18, s10
	s_addc_u32 s99, s19, s11
	s_add_u32 s100, s20, s10
	s_addc_u32 s101, s21, s11
	s_add_i32 s14, s29, s89
	s_mov_b32 m0, s14
	ds_read_b128 v[178:181], v149 offset:16384
	ds_read_b128 v[182:185], v149 offset:17408
	ds_read_b128 v[186:189], v149 offset:18432
	ds_read_b128 v[190:193], v149 offset:19456
	ds_read_b128 v[194:197], v149 offset:20480
	ds_read_b128 v[198:201], v149 offset:21504
	ds_read_b128 v[202:205], v149 offset:22528
	ds_read_b128 v[206:209], v149 offset:23552
	global_load_lds_dwordx4 v128, s[18:19]
	s_add_i32 m0, s14, 0x2000
	s_add_u32 s14, s18, 0x160000
	s_addc_u32 s15, s19, 0
	s_add_i32 s44, s36, s89
	global_load_lds_dwordx4 v130, s[18:19]
	s_mov_b32 m0, s44
	s_nop 0
	global_load_lds_dwordx4 v128, s[14:15]
	s_add_i32 m0, s44, 0x2000
	s_nop 0
	global_load_lds_dwordx4 v130, s[14:15]
	s_mov_b32 m0, s3
	s_nop 0
	global_load_lds_dwordx4 v128, s[20:21]
	s_mov_b32 m0, s22
	s_nop 0
	global_load_lds_dwordx4 v130, s[20:21]
	s_waitcnt vmcnt(8)
	s_waitcnt lgkmcnt(0)
	s_barrier
	s_setprio 3
	s_waitcnt lgkmcnt(0)
	v_mfma_f32_16x16x32_bf16 v[60:63], v[140:143], v[178:181], v[60:63]
	v_mfma_f32_16x16x32_bf16 v[56:59], v[154:157], v[178:181], v[56:59]
	v_mfma_f32_16x16x32_bf16 v[48:51], v[140:143], v[186:189], v[48:51]
	v_mfma_f32_16x16x32_bf16 v[40:43], v[154:157], v[186:189], v[40:43]
	v_mfma_f32_16x16x32_bf16 v[32:35], v[140:143], v[194:197], v[32:35]
	v_mfma_f32_16x16x32_bf16 v[24:27], v[154:157], v[194:197], v[24:27]
	v_mfma_f32_16x16x32_bf16 v[16:19], v[140:143], v[202:205], v[16:19]
	v_mfma_f32_16x16x32_bf16 v[8:11], v[154:157], v[202:205], v[8:11]
	v_mfma_f32_16x16x32_bf16 v[60:63], v[150:153], v[182:185], v[60:63]
	v_mfma_f32_16x16x32_bf16 v[56:59], v[158:161], v[182:185], v[56:59]
	v_mfma_f32_16x16x32_bf16 v[48:51], v[150:153], v[190:193], v[48:51]
	v_mfma_f32_16x16x32_bf16 v[40:43], v[158:161], v[190:193], v[40:43]
	v_mfma_f32_16x16x32_bf16 v[32:35], v[150:153], v[198:201], v[32:35]
	v_mfma_f32_16x16x32_bf16 v[24:27], v[158:161], v[198:201], v[24:27]
	v_mfma_f32_16x16x32_bf16 v[16:19], v[150:153], v[206:209], v[16:19]
	v_mfma_f32_16x16x32_bf16 v[8:11], v[158:161], v[206:209], v[8:11]
	s_setprio 0
	s_setprio 3
	v_mfma_f32_16x16x32_bf16 v[52:55], v[162:165], v[178:181], v[52:55]
	v_mfma_f32_16x16x32_bf16 v[44:47], v[170:173], v[178:181], v[44:47]
	v_mfma_f32_16x16x32_bf16 v[36:39], v[162:165], v[186:189], v[36:39]
	v_mfma_f32_16x16x32_bf16 v[28:31], v[170:173], v[186:189], v[28:31]
	v_mfma_f32_16x16x32_bf16 v[20:23], v[162:165], v[194:197], v[20:23]
	v_mfma_f32_16x16x32_bf16 v[12:15], v[170:173], v[194:197], v[12:15]
	v_mfma_f32_16x16x32_bf16 v[4:7], v[162:165], v[202:205], v[4:7]
	v_mfma_f32_16x16x32_bf16 v[0:3], v[170:173], v[202:205], v[0:3]
	v_mfma_f32_16x16x32_bf16 v[52:55], v[166:169], v[182:185], v[52:55]
	v_mfma_f32_16x16x32_bf16 v[44:47], v[174:177], v[182:185], v[44:47]
	v_mfma_f32_16x16x32_bf16 v[36:39], v[166:169], v[190:193], v[36:39]
	v_mfma_f32_16x16x32_bf16 v[28:31], v[174:177], v[190:193], v[28:31]
	v_mfma_f32_16x16x32_bf16 v[20:23], v[166:169], v[198:201], v[20:23]
	v_mfma_f32_16x16x32_bf16 v[12:15], v[174:177], v[198:201], v[12:15]
	v_mfma_f32_16x16x32_bf16 v[4:7], v[166:169], v[206:209], v[4:7]
	v_mfma_f32_16x16x32_bf16 v[0:3], v[174:177], v[206:209], v[0:3]
	s_setprio 0
	s_barrier
	s_add_i32 s44, 0, 0x18000
	s_add_i32 s45, 0, 0x1c000
	v_add_u32_e32 v158, s44, v145
	v_add_u32_e32 v174, s45, v145
	ds_read_b128 v[140:143], v158
	ds_read_b128 v[150:153], v158 offset:1024
	ds_read_b128 v[154:157], v158 offset:2048
	ds_read_b128 v[158:161], v158 offset:3072
	ds_read_b128 v[162:165], v174
	ds_read_b128 v[166:169], v174 offset:1024
	ds_read_b128 v[170:173], v174 offset:2048
	ds_read_b128 v[174:177], v174 offset:3072
	s_add_u32 s14, s20, 0x160000
	s_addc_u32 s15, s21, 0
	s_mov_b32 m0, s23
	ds_read_b128 v[178:181], v149 offset:32768
	ds_read_b128 v[182:185], v149 offset:33792
	ds_read_b128 v[186:189], v149 offset:34816
	ds_read_b128 v[190:193], v149 offset:35840
	ds_read_b128 v[194:197], v149 offset:36864
	ds_read_b128 v[198:201], v149 offset:37888
	ds_read_b128 v[202:205], v149 offset:38912
	ds_read_b128 v[206:209], v149 offset:39936
	global_load_lds_dwordx4 v128, s[14:15]
	s_mov_b32 m0, s25
	s_nop 0
	global_load_lds_dwordx4 v130, s[14:15]
	s_waitcnt vmcnt(8)
	s_waitcnt lgkmcnt(0)
	s_barrier
	s_setprio 3
	s_waitcnt lgkmcnt(0)
	v_mfma_f32_16x16x32_bf16 v[124:127], v[140:143], v[178:181], v[124:127]
	v_mfma_f32_16x16x32_bf16 v[120:123], v[154:157], v[178:181], v[120:123]
	v_mfma_f32_16x16x32_bf16 v[112:115], v[140:143], v[186:189], v[112:115]
	v_mfma_f32_16x16x32_bf16 v[104:107], v[154:157], v[186:189], v[104:107]
	v_mfma_f32_16x16x32_bf16 v[96:99], v[140:143], v[194:197], v[96:99]
	v_mfma_f32_16x16x32_bf16 v[88:91], v[154:157], v[194:197], v[88:91]
	v_mfma_f32_16x16x32_bf16 v[80:83], v[140:143], v[202:205], v[80:83]
	v_mfma_f32_16x16x32_bf16 v[72:75], v[154:157], v[202:205], v[72:75]
	v_mfma_f32_16x16x32_bf16 v[124:127], v[150:153], v[182:185], v[124:127]
	v_mfma_f32_16x16x32_bf16 v[120:123], v[158:161], v[182:185], v[120:123]
	v_mfma_f32_16x16x32_bf16 v[112:115], v[150:153], v[190:193], v[112:115]
	v_mfma_f32_16x16x32_bf16 v[104:107], v[158:161], v[190:193], v[104:107]
	v_mfma_f32_16x16x32_bf16 v[96:99], v[150:153], v[198:201], v[96:99]
	v_mfma_f32_16x16x32_bf16 v[88:91], v[158:161], v[198:201], v[88:91]
	v_mfma_f32_16x16x32_bf16 v[80:83], v[150:153], v[206:209], v[80:83]
	v_mfma_f32_16x16x32_bf16 v[72:75], v[158:161], v[206:209], v[72:75]
	s_setprio 0
	s_setprio 3
	v_mfma_f32_16x16x32_bf16 v[116:119], v[162:165], v[178:181], v[116:119]
	v_mfma_f32_16x16x32_bf16 v[108:111], v[170:173], v[178:181], v[108:111]
	v_mfma_f32_16x16x32_bf16 v[100:103], v[162:165], v[186:189], v[100:103]
	v_mfma_f32_16x16x32_bf16 v[92:95], v[170:173], v[186:189], v[92:95]
	v_mfma_f32_16x16x32_bf16 v[84:87], v[162:165], v[194:197], v[84:87]
	v_mfma_f32_16x16x32_bf16 v[76:79], v[170:173], v[194:197], v[76:79]
	v_mfma_f32_16x16x32_bf16 v[68:71], v[162:165], v[202:205], v[68:71]
	v_mfma_f32_16x16x32_bf16 v[64:67], v[170:173], v[202:205], v[64:67]
	v_mfma_f32_16x16x32_bf16 v[116:119], v[166:169], v[182:185], v[116:119]
	v_mfma_f32_16x16x32_bf16 v[108:111], v[174:177], v[182:185], v[108:111]
	v_mfma_f32_16x16x32_bf16 v[100:103], v[166:169], v[190:193], v[100:103]
	v_mfma_f32_16x16x32_bf16 v[92:95], v[174:177], v[190:193], v[92:95]
	v_mfma_f32_16x16x32_bf16 v[84:87], v[166:169], v[198:201], v[84:87]
	v_mfma_f32_16x16x32_bf16 v[76:79], v[174:177], v[198:201], v[76:79]
	v_mfma_f32_16x16x32_bf16 v[68:71], v[166:169], v[206:209], v[68:71]
	v_mfma_f32_16x16x32_bf16 v[64:67], v[174:177], v[206:209], v[64:67]
	s_setprio 0
	s_barrier
	s_add_i32 s14, s44, s89
	s_mov_b32 m0, s14
	ds_read_b128 v[178:181], v149 offset:49152
	ds_read_b128 v[182:185], v149 offset:50176
	ds_read_b128 v[186:189], v149 offset:51200
	ds_read_b128 v[190:193], v149 offset:52224
	ds_read_b128 v[194:197], v149 offset:53248
	ds_read_b128 v[198:201], v149 offset:54272
	ds_read_b128 v[202:205], v149 offset:55296
	ds_read_b128 v[206:209], v149 offset:56320
	global_load_lds_dwordx4 v128, s[98:99]
	s_add_i32 m0, s14, 0x2000
	s_add_u32 s14, s18, 0x160080
	s_addc_u32 s15, s19, 0
	s_add_i32 s18, s45, s89
	global_load_lds_dwordx4 v130, s[98:99]
	s_mov_b32 m0, s18
	s_nop 0
	global_load_lds_dwordx4 v128, s[14:15]
	s_add_i32 m0, s18, 0x2000
	s_nop 0
	global_load_lds_dwordx4 v130, s[14:15]
	s_mov_b32 m0, s27
	s_nop 0
	global_load_lds_dwordx4 v128, s[100:101]
	s_mov_b32 m0, s28
	s_nop 0
	global_load_lds_dwordx4 v130, s[100:101]
	s_waitcnt vmcnt(8)
	s_waitcnt lgkmcnt(0)
	s_barrier
	s_setprio 3
	s_waitcnt lgkmcnt(0)
	v_mfma_f32_16x16x32_bf16 v[60:63], v[140:143], v[178:181], v[60:63]
	v_mfma_f32_16x16x32_bf16 v[56:59], v[154:157], v[178:181], v[56:59]
	v_mfma_f32_16x16x32_bf16 v[48:51], v[140:143], v[186:189], v[48:51]
	v_mfma_f32_16x16x32_bf16 v[40:43], v[154:157], v[186:189], v[40:43]
	v_mfma_f32_16x16x32_bf16 v[32:35], v[140:143], v[194:197], v[32:35]
	v_mfma_f32_16x16x32_bf16 v[24:27], v[154:157], v[194:197], v[24:27]
	v_mfma_f32_16x16x32_bf16 v[16:19], v[140:143], v[202:205], v[16:19]
	v_mfma_f32_16x16x32_bf16 v[8:11], v[154:157], v[202:205], v[8:11]
	v_mfma_f32_16x16x32_bf16 v[60:63], v[150:153], v[182:185], v[60:63]
	v_mfma_f32_16x16x32_bf16 v[56:59], v[158:161], v[182:185], v[56:59]
	v_mfma_f32_16x16x32_bf16 v[48:51], v[150:153], v[190:193], v[48:51]
	v_mfma_f32_16x16x32_bf16 v[40:43], v[158:161], v[190:193], v[40:43]
	v_mfma_f32_16x16x32_bf16 v[32:35], v[150:153], v[198:201], v[32:35]
	v_mfma_f32_16x16x32_bf16 v[24:27], v[158:161], v[198:201], v[24:27]
	v_mfma_f32_16x16x32_bf16 v[16:19], v[150:153], v[206:209], v[16:19]
	v_mfma_f32_16x16x32_bf16 v[8:11], v[158:161], v[206:209], v[8:11]
	s_setprio 0
	s_setprio 3
	v_mfma_f32_16x16x32_bf16 v[52:55], v[162:165], v[178:181], v[52:55]
	v_mfma_f32_16x16x32_bf16 v[44:47], v[170:173], v[178:181], v[44:47]
	v_mfma_f32_16x16x32_bf16 v[36:39], v[162:165], v[186:189], v[36:39]
	v_mfma_f32_16x16x32_bf16 v[28:31], v[170:173], v[186:189], v[28:31]
	v_mfma_f32_16x16x32_bf16 v[20:23], v[162:165], v[194:197], v[20:23]
	v_mfma_f32_16x16x32_bf16 v[12:15], v[170:173], v[194:197], v[12:15]
	v_mfma_f32_16x16x32_bf16 v[4:7], v[162:165], v[202:205], v[4:7]
	v_mfma_f32_16x16x32_bf16 v[0:3], v[170:173], v[202:205], v[0:3]
	v_mfma_f32_16x16x32_bf16 v[52:55], v[166:169], v[182:185], v[52:55]
	v_mfma_f32_16x16x32_bf16 v[44:47], v[174:177], v[182:185], v[44:47]
	v_mfma_f32_16x16x32_bf16 v[36:39], v[166:169], v[190:193], v[36:39]
	v_mfma_f32_16x16x32_bf16 v[28:31], v[174:177], v[190:193], v[28:31]
	v_mfma_f32_16x16x32_bf16 v[20:23], v[166:169], v[198:201], v[20:23]
	v_mfma_f32_16x16x32_bf16 v[12:15], v[174:177], v[198:201], v[12:15]
	v_mfma_f32_16x16x32_bf16 v[4:7], v[166:169], v[206:209], v[4:7]
	v_mfma_f32_16x16x32_bf16 v[0:3], v[174:177], v[206:209], v[0:3]
	s_setprio 0
	s_barrier
	s_add_i32 s43, s43, 2
	s_add_u32 s41, s41, 0x100
	s_addc_u32 s42, s42, 0
	s_cmpk_gt_u32 s43, 0x55
	s_mov_b64 s[14:15], s[16:17]
	s_cbranch_scc0 .LBB0_926
	s_and_b64 vcc, exec, s[64:65]
	s_cbranch_vccz .LBB0_929
	s_barrier
